# v6: mLSTM and GLA chunk loops: staging waits counted (vmcnt(32)) so the finished chunk's output stores need not be acknowledged first; flat ops of both phases converted to global
# speedup vs baseline: 1.0036x; 1.0036x over previous
.LBB0_353:
	s_and_b64 s[20:21], vcc, exec
	s_cselect_b32 s0, s23, s1
	v_lshl_add_u32 v10, s0, 6, v2
	v_ashrrev_i32_e32 v11, 31, v10
	v_lshlrev_b64 v[10:11], 6, v[10:11]
	v_lshl_add_u64 v[10:11], s[34:35], 0, v[10:11]
	global_load_dword v12, v[10:11], off offset:16
	global_load_dword v13, v[10:11], off
	s_mov_b32 s0, 0xbfb8aa3b
	s_add_i32 s1, s1, -8
	s_waitcnt vmcnt(0) lgkmcnt(0)
	v_mul_f32_e64 v11, |v12|, s0
	v_max_f32_e32 v10, v12, v12
	v_exp_f32_e32 v12, v11
	v_min_f32_e32 v14, 0, v10
	s_add_i32 s0, s23, 8
	s_cmp_gt_u32 s23, 23
	v_add_f32_e32 v15, 1.0, v12
	v_add_f32_e32 v16, -1.0, v15
	v_frexp_mant_f32_e32 v17, v15
	v_cvt_f64_f32_e32 v[10:11], v15
	v_sub_f32_e32 v18, v16, v15
	v_frexp_exp_i32_f64_e32 v10, v[10:11]
	v_cmp_gt_f32_e64 s[20:21], s53, v17
	v_sub_f32_e32 v16, v12, v16
	v_add_f32_e32 v11, 1.0, v18
	v_subbrev_co_u32_e64 v10, s[20:21], 0, v10, s[20:21]
	v_add_f32_e32 v11, v16, v11
	v_sub_u32_e32 v16, 0, v10
	v_cvt_f32_i32_e32 v10, v10
	v_ldexp_f32 v15, v15, v16
	v_ldexp_f32 v11, v11, v16
	v_add_f32_e32 v16, -1.0, v15
	v_add_f32_e32 v17, 1.0, v15
	v_add_f32_e32 v18, 1.0, v16
	v_add_f32_e32 v19, -1.0, v17
	v_sub_f32_e32 v18, v15, v18
	v_sub_f32_e32 v15, v15, v19
	v_mul_f32_e32 v19, 0x3f317218, v10
	v_add_f32_e32 v18, v11, v18
	v_add_f32_e32 v11, v11, v15
	v_fma_f32 v15, v10, s54, -v19
	v_add_f32_e32 v20, v16, v18
	v_add_f32_e32 v21, v17, v11
	v_fmac_f32_e32 v15, 0xb102e308, v10
	v_sub_f32_e32 v10, v20, v16
	v_sub_f32_e32 v16, v21, v17
	v_rcp_f32_e32 v17, v21
	v_add_f32_e32 v22, v19, v15
	v_sub_f32_e32 v11, v11, v16
	v_sub_f32_e32 v16, v22, v19
	v_sub_f32_e32 v15, v15, v16
	v_mul_f32_e32 v16, v20, v17
	v_sub_f32_e32 v10, v18, v10
	v_mul_f32_e32 v18, v21, v16
	v_fma_f32 v19, v16, v21, -v18
	v_fmac_f32_e32 v19, v16, v11
	v_add_f32_e32 v23, v18, v19
	v_sub_f32_e32 v24, v20, v23
	v_sub_f32_e32 v18, v23, v18
	v_sub_f32_e32 v20, v20, v24
	v_sub_f32_e32 v18, v18, v19
	v_sub_f32_e32 v19, v20, v23
	v_add_f32_e32 v10, v10, v19
	v_add_f32_e32 v10, v18, v10
	v_add_f32_e32 v18, v24, v10
	v_mul_f32_e32 v19, v17, v18
	v_sub_f32_e32 v20, v24, v18
	v_mul_f32_e32 v23, v21, v19
	v_add_f32_e32 v10, v10, v20
	v_add_f32_e32 v20, v16, v19
	v_fma_f32 v21, v19, v21, -v23
	v_sub_f32_e32 v16, v20, v16
	v_fmac_f32_e32 v21, v19, v11
	v_sub_f32_e32 v11, v19, v16
	v_add_f32_e32 v16, v23, v21
	v_sub_f32_e32 v19, v16, v23
	v_sub_f32_e32 v23, v18, v16
	v_sub_f32_e32 v18, v18, v23
	v_sub_f32_e32 v16, v18, v16
	v_sub_f32_e32 v19, v19, v21
	v_add_f32_e32 v10, v10, v16
	v_add_f32_e32 v10, v19, v10
	v_add_f32_e32 v10, v23, v10
	v_mul_f32_e32 v10, v17, v10
	v_add_f32_e32 v10, v11, v10
	v_add_f32_e32 v11, v20, v10
	v_mul_f32_e32 v16, v11, v11
	v_fmamk_f32 v19, v16, 0x3e9b6dac, v173
	v_sub_f32_e32 v17, v11, v20
	v_ldexp_f32 v18, v11, 1
	v_mul_f32_e32 v11, v11, v16
	v_fmaak_f32 v16, v16, v19, 0x3f2aaada
	v_mul_f32_e32 v11, v11, v16
	v_add_f32_e32 v16, v18, v11
	v_sub_f32_e32 v10, v10, v17
	v_sub_f32_e32 v17, v16, v18
	v_ldexp_f32 v10, v10, 1
	v_sub_f32_e32 v11, v11, v17
	v_add_f32_e32 v10, v10, v11
	v_add_f32_e32 v11, v16, v10
	v_sub_f32_e32 v16, v11, v16
	v_add_f32_e32 v17, v22, v11
	v_sub_f32_e32 v10, v10, v16
	v_sub_f32_e32 v16, v17, v22
	v_sub_f32_e32 v18, v17, v16
	v_sub_f32_e32 v11, v11, v16
	v_add_f32_e32 v16, v15, v10
	v_sub_f32_e32 v18, v22, v18
	v_sub_f32_e32 v19, v16, v15
	v_add_f32_e32 v11, v11, v18
	v_sub_f32_e32 v18, v16, v19
	v_sub_f32_e32 v10, v10, v19
	v_sub_f32_e32 v15, v15, v18
	v_add_f32_e32 v11, v16, v11
	v_add_f32_e32 v10, v10, v15
	v_add_f32_e32 v15, v17, v11
	v_sub_f32_e32 v16, v15, v17
	v_sub_f32_e32 v11, v11, v16
	v_add_f32_e32 v10, v10, v11
	v_add_f32_e32 v10, v15, v10
	v_cmp_neq_f32_e64 s[20:21], s55, v12
	v_add_u32_e32 v15, 0xffffe000, v9
	s_mov_b32 s23, s0
	v_cndmask_b32_e64 v10, v182, v10, s[20:21]
	v_cmp_ngt_f32_e64 s[20:21], -1.0, v12
	s_nop 1
	v_cndmask_b32_e64 v10, v183, v10, s[20:21]
	v_cmp_neq_f32_e64 s[20:21], -1.0, v12
	s_nop 1
	v_cndmask_b32_e64 v10, v184, v10, s[20:21]
	v_cmp_lt_f32_e64 s[20:21], |v12|, s56
	s_nop 1
	v_cndmask_b32_e64 v10, v10, v12, s[20:21]
	v_sub_f32_e32 v10, v14, v10
	ds_bpermute_b32 v11, v3, v10
	v_add_u32_e32 v14, 0xffffc000, v9
	s_waitcnt lgkmcnt(0)
	v_add_f32_e32 v11, v10, v11
	v_cndmask_b32_e64 v10, v11, v10, s[8:9]
	ds_bpermute_b32 v11, v4, v10
	s_waitcnt lgkmcnt(0)
	v_add_f32_e32 v11, v10, v11
	v_cndmask_b32_e64 v10, v11, v10, s[10:11]
	ds_bpermute_b32 v11, v5, v10
	s_waitcnt lgkmcnt(0)
	v_add_f32_e32 v11, v10, v11
	v_cndmask_b32_e64 v10, v11, v10, s[12:13]
	ds_bpermute_b32 v11, v6, v10
	s_waitcnt lgkmcnt(0)
	v_add_f32_e32 v11, v10, v11
	v_cndmask_b32_e64 v10, v11, v10, s[14:15]
	ds_bpermute_b32 v11, v7, v10
	s_waitcnt lgkmcnt(0)
	v_add_f32_e32 v11, v10, v11
	v_cndmask_b32_e64 v10, v11, v10, s[16:17]
	ds_bpermute_b32 v11, v8, v10
	s_waitcnt lgkmcnt(0)
	v_add_f32_e32 v11, v10, v11
	v_cndmask_b32_e64 v10, v11, v10, s[18:19]
	v_sub_f32_e32 v11, v13, v10
	ds_bpermute_b32 v12, v3, v11
	ds_write_b32 v14, v10
	ds_write_b32 v15, v11
	s_waitcnt lgkmcnt(2)
	v_max_f32_e32 v12, v12, v12
	v_max_f32_e32 v12, v11, v12
	v_cndmask_b32_e64 v12, v12, v11, s[8:9]
	ds_bpermute_b32 v13, v4, v12
	s_waitcnt lgkmcnt(0)
	v_max_f32_e32 v13, v13, v13
	v_max_f32_e32 v13, v12, v13
	v_cndmask_b32_e64 v12, v13, v12, s[10:11]
	ds_bpermute_b32 v13, v5, v12
	s_waitcnt lgkmcnt(0)
	v_max_f32_e32 v13, v13, v13
	v_max_f32_e32 v13, v12, v13
	v_cndmask_b32_e64 v12, v13, v12, s[12:13]
	ds_bpermute_b32 v13, v6, v12
	s_waitcnt lgkmcnt(0)
	v_max_f32_e32 v13, v13, v13
	v_max_f32_e32 v13, v12, v13
	v_cndmask_b32_e64 v12, v13, v12, s[14:15]
	ds_bpermute_b32 v13, v7, v12
	s_waitcnt lgkmcnt(0)
	v_max_f32_e32 v13, v13, v13
	v_max_f32_e32 v13, v12, v13
	v_cndmask_b32_e64 v12, v13, v12, s[16:17]
	ds_bpermute_b32 v13, v8, v12
	v_max_f32_e32 v10, v12, v12
	s_waitcnt lgkmcnt(0)
	v_max_f32_e32 v11, v13, v13
	v_max_f32_e32 v10, v10, v11
	v_cndmask_b32_e64 v10, v10, v12, s[18:19]
	ds_write_b32 v9, v10
	v_add_u32_e32 v9, 0x800, v9
	s_cbranch_scc0 .LBB0_353
.LBB0_354:
	s_ashr_i32 s23, s22, 31
	s_lshl_b64 s[0:1], s[22:23], 27
	s_add_u32 s34, s48, s0
	s_addc_u32 s35, s49, s1
	s_cmpk_lt_u32 s69, 0x80
	s_cselect_b64 s[20:21], -1, 0
	s_and_b64 s[0:1], s[20:21], exec
	s_cselect_b32 s0, 0, 0x7c0
	v_cndmask_b32_e64 v2, v161, v160, s[20:21]
	s_or_b32 s38, s72, s0
	v_add_u32_e32 v4, s38, v2
	v_mov_b64_e32 v[2:3], s[30:31]
	v_mad_i64_i32 v[4:5], s[0:1], v4, s57, v[2:3]
	s_lshl_b32 s0, s25, 8
	s_mov_b32 s1, s24
	v_lshl_add_u64 v[4:5], v[4:5], 0, s[0:1]
	v_mov_b32_e32 v153, v151
	v_lshl_add_u64 v[4:5], v[4:5], 0, v[152:153]
	s_waitcnt vmcnt(0)
	global_load_dwordx4 v[98:101], v[4:5], off
	global_load_dwordx4 v[102:105], v[4:5], off offset:1024
	v_cndmask_b32_e64 v4, v163, v162, s[20:21]
	v_add_u32_e32 v4, s38, v4
	v_mad_i64_i32 v[4:5], s[22:23], v4, s57, v[2:3]
	v_lshl_add_u64 v[4:5], v[4:5], 0, s[0:1]
	v_lshl_add_u64 v[4:5], v[4:5], 0, v[152:153]
	global_load_dwordx4 v[106:109], v[4:5], off
	global_load_dwordx4 v[110:113], v[4:5], off offset:1024
	v_cndmask_b32_e64 v4, v165, v164, s[20:21]
	v_add_u32_e32 v4, s38, v4
	v_cndmask_b32_e64 v6, v167, v166, s[20:21]
	v_mad_i64_i32 v[4:5], s[22:23], v4, s57, v[2:3]
	s_lshl_b32 s36, s25, 9
	s_mov_b32 s37, s24
	v_add_u32_e32 v6, s38, v6
	v_lshl_add_u64 v[4:5], v[4:5], 0, s[36:37]
	v_mov_b32_e32 v155, v151
	v_mad_i64_i32 v[6:7], s[22:23], v6, s57, v[2:3]
	v_lshl_add_u64 v[4:5], v[4:5], 0, v[154:155]
	v_lshl_add_u64 v[6:7], v[6:7], 0, s[36:37]
	v_lshl_add_u64 v[6:7], v[6:7], 0, v[154:155]
	global_load_dwordx4 v[114:117], v[4:5], off offset:2048
	global_load_dwordx4 v[118:121], v[6:7], off offset:2048
	v_cndmask_b32_e64 v4, v169, v168, s[20:21]
	v_add_u32_e32 v4, s38, v4
	v_cndmask_b32_e64 v6, v171, v170, s[20:21]
	v_mad_i64_i32 v[4:5], s[22:23], v4, s57, v[2:3]
	v_add_u32_e32 v6, s38, v6
	v_lshl_add_u64 v[4:5], v[4:5], 0, s[36:37]
	v_mad_i64_i32 v[2:3], s[22:23], v6, s57, v[2:3]
	v_lshl_add_u64 v[4:5], v[4:5], 0, v[154:155]
	v_lshl_add_u64 v[2:3], v[2:3], 0, s[36:37]
	v_lshl_add_u64 v[2:3], v[2:3], 0, v[154:155]
	global_load_dwordx4 v[122:125], v[4:5], off offset:2048
	global_load_dwordx4 v[126:129], v[2:3], off offset:2048
	s_add_u32 s1, s34, s36
	s_addc_u32 s23, s35, 0
	s_add_u32 s22, s1, s58
	s_addc_u32 s23, s23, 0
	s_add_u32 s34, s30, s0
	s_addc_u32 s35, s31, 0
	s_add_u32 s36, s30, s36
	s_mov_b32 s73, 0
	s_addc_u32 s37, s31, 0
	s_mov_b32 s76, 30
	v_mov_b32_e32 v155, 0
	v_mov_b32_e32 v2, 0
	v_mov_b32_e32 v3, 0
	v_mov_b32_e32 v4, 0
	v_mov_b32_e32 v5, 0
	v_mov_b32_e32 v6, 0
	v_mov_b32_e32 v7, 0
	v_mov_b32_e32 v8, 0
	v_mov_b32_e32 v9, 0
	v_mov_b32_e32 v10, 0
	v_mov_b32_e32 v11, 0
	v_mov_b32_e32 v12, 0
	v_mov_b32_e32 v13, 0
	v_mov_b32_e32 v14, 0
	v_mov_b32_e32 v15, 0
	v_mov_b32_e32 v16, 0
	v_mov_b32_e32 v17, 0
	v_mov_b32_e32 v18, 0
	v_mov_b32_e32 v19, 0
	v_mov_b32_e32 v20, 0
	v_mov_b32_e32 v21, 0
	v_mov_b32_e32 v22, 0
	v_mov_b32_e32 v23, 0
	v_mov_b32_e32 v24, 0
	v_mov_b32_e32 v25, 0
	v_mov_b32_e32 v26, 0
	v_mov_b32_e32 v27, 0
	v_mov_b32_e32 v28, 0
	v_mov_b32_e32 v29, 0
	v_mov_b32_e32 v30, 0
	v_mov_b32_e32 v31, 0
	v_mov_b32_e32 v32, 0
	v_mov_b32_e32 v33, 0
	v_mov_b32_e32 v34, 0
	v_mov_b32_e32 v35, 0
	v_mov_b32_e32 v36, 0
	v_mov_b32_e32 v37, 0
	v_mov_b32_e32 v38, 0
	v_mov_b32_e32 v39, 0
	v_mov_b32_e32 v40, 0
	v_mov_b32_e32 v41, 0
	v_mov_b32_e32 v42, 0
	v_mov_b32_e32 v43, 0
	v_mov_b32_e32 v44, 0
	v_mov_b32_e32 v45, 0
	v_mov_b32_e32 v46, 0
	v_mov_b32_e32 v47, 0
	v_mov_b32_e32 v48, 0
	v_mov_b32_e32 v49, 0
	v_mov_b32_e32 v50, 0
	v_mov_b32_e32 v51, 0
	v_mov_b32_e32 v52, 0
	v_mov_b32_e32 v53, 0
	v_mov_b32_e32 v54, 0
	v_mov_b32_e32 v55, 0
	v_mov_b32_e32 v56, 0
	v_mov_b32_e32 v57, 0
	v_mov_b32_e32 v58, 0
	v_mov_b32_e32 v59, 0
	v_mov_b32_e32 v60, 0
	v_mov_b32_e32 v61, 0
	v_mov_b32_e32 v62, 0
	v_mov_b32_e32 v63, 0
	v_mov_b32_e32 v64, 0
	v_mov_b32_e32 v65, 0
	s_mov_b32 s77, 0
	s_mov_b32 s80, 0
	s_waitcnt lgkmcnt(0)
	s_waitcnt vmcnt(0)
	s_barrier
	s_branch .LBB0_356
.LBB0_355:
	s_or_b64 exec, exec, s[38:39]
	v_lshrrev_b32_e32 v136, 3, v134
	v_and_b32_e32 v137, 4, v136
	v_lshl_add_u32 v131, v137, 2, 0
	v_and_b32_e32 v130, 31, v134
	v_add_u32_e32 v138, 0x16000, v131
	s_add_i32 s25, s76, 1
	v_lshlrev_b32_e32 v150, 1, v130
	ds_read_b128 v[130:133], v138
	s_and_b64 s[0:1], s[20:21], exec
	s_cselect_b32 s0, s80, s25
	s_lshl_b32 s25, s0, 6
	s_add_i32 s0, s79, 0x180fc
	v_mov_b32_e32 v139, s0
	ds_read_b32 v139, v139
	s_waitcnt lgkmcnt(0)
	v_mul_f32_e32 v66, v66, v130
	v_bitop3_b32 v130, v136, 63, 4 bitop3:0x6c
	v_cndmask_b32_e64 v130, v130, v137, s[20:21]
	v_or_b32_e32 v130, s72, v130
	v_lshl_add_u64 v[134:135], s[22:23], 0, v[150:151]
	v_or_b32_e32 v150, s25, v130
	v_lshlrev_b64 v[140:141], 11, v[150:151]
	v_cvt_pk_bf16_f32 v66, v66, s0
	v_lshl_add_u64 v[140:141], v[134:135], 0, v[140:141]
	v_mul_f32_e32 v67, v67, v131
	global_store_short v[140:141], v66, off
	v_or_b32_e32 v66, 1, v137
	v_cvt_pk_bf16_f32 v130, v67, s0
	v_bitop3_b32 v67, v136, 62, 4 bitop3:0x6c
	v_cndmask_b32_e64 v66, v67, v66, s[20:21]
	v_or_b32_e32 v66, s72, v66
	v_or_b32_e32 v150, s25, v66
	v_lshlrev_b64 v[66:67], 11, v[150:151]
	v_lshl_add_u64 v[66:67], v[134:135], 0, v[66:67]
	global_store_short v[66:67], v130, off
	v_mul_f32_e32 v67, v68, v132
	v_or_b32_e32 v66, 2, v137
	v_cvt_pk_bf16_f32 v68, v67, s0
	v_bitop3_b32 v67, v136, 61, 4 bitop3:0x6c
	v_cndmask_b32_e64 v66, v67, v66, s[20:21]
	v_or_b32_e32 v66, s72, v66
	v_or_b32_e32 v150, s25, v66
	v_lshlrev_b64 v[66:67], 11, v[150:151]
	v_lshl_add_u64 v[66:67], v[134:135], 0, v[66:67]
	global_store_short v[66:67], v68, off
	v_mul_f32_e32 v67, v69, v133
	v_or_b32_e32 v66, 3, v137
	v_cvt_pk_bf16_f32 v68, v67, s0
	v_bitop3_b32 v67, v136, 60, 4 bitop3:0x6c
	v_cndmask_b32_e64 v66, v67, v66, s[20:21]
	v_or_b32_e32 v66, s72, v66
	v_or_b32_e32 v150, s25, v66
	v_lshlrev_b64 v[66:67], 11, v[150:151]
	v_lshl_add_u64 v[66:67], v[134:135], 0, v[66:67]
	global_store_short v[66:67], v68, off
	ds_read_b128 v[66:69], v138 offset:32
	v_or_b32_e32 v130, 8, v137
	s_add_i32 s76, s76, -1
	s_addk_i32 s77, 0x100
	s_add_i32 s73, s73, 64
	s_waitcnt lgkmcnt(0)
	v_mul_f32_e32 v66, v70, v66
	v_bitop3_b32 v70, v136, 55, 4 bitop3:0x6c
	v_cndmask_b32_e64 v70, v70, v130, s[20:21]
	v_or_b32_e32 v70, s72, v70
	v_or_b32_e32 v150, s25, v70
	v_lshlrev_b64 v[130:131], 11, v[150:151]
	v_cvt_pk_bf16_f32 v66, v66, s0
	v_lshl_add_u64 v[130:131], v[134:135], 0, v[130:131]
	v_mul_f32_e32 v67, v71, v67
	global_store_short v[130:131], v66, off
	v_or_b32_e32 v66, 9, v137
	v_cvt_pk_bf16_f32 v70, v67, s0
	v_bitop3_b32 v67, v136, 54, 4 bitop3:0x6c
	v_cndmask_b32_e64 v66, v67, v66, s[20:21]
	v_or_b32_e32 v66, s72, v66
	v_or_b32_e32 v150, s25, v66
	v_lshlrev_b64 v[66:67], 11, v[150:151]
	v_lshl_add_u64 v[66:67], v[134:135], 0, v[66:67]
	global_store_short v[66:67], v70, off
	v_mul_f32_e32 v67, v72, v68
	v_or_b32_e32 v66, 10, v137
	v_cvt_pk_bf16_f32 v68, v67, s0
	v_bitop3_b32 v67, v136, 53, 4 bitop3:0x6c
	v_cndmask_b32_e64 v66, v67, v66, s[20:21]
	v_or_b32_e32 v66, s72, v66
	v_or_b32_e32 v150, s25, v66
	v_lshlrev_b64 v[66:67], 11, v[150:151]
	v_lshl_add_u64 v[66:67], v[134:135], 0, v[66:67]
	global_store_short v[66:67], v68, off
	v_mul_f32_e32 v67, v73, v69
	v_or_b32_e32 v66, 11, v137
	v_cvt_pk_bf16_f32 v68, v67, s0
	v_bitop3_b32 v67, v136, 52, 4 bitop3:0x6c
	v_cndmask_b32_e64 v66, v67, v66, s[20:21]
	v_or_b32_e32 v66, s72, v66
	v_or_b32_e32 v150, s25, v66
	v_lshlrev_b64 v[66:67], 11, v[150:151]
	v_lshl_add_u64 v[66:67], v[134:135], 0, v[66:67]
	global_store_short v[66:67], v68, off
	ds_read_b128 v[66:69], v138 offset:64
	v_or_b32_e32 v70, 16, v137
	v_bitop3_b32 v71, v136, 47, 4 bitop3:0x6c
	v_cndmask_b32_e64 v70, v71, v70, s[20:21]
	v_or_b32_e32 v70, s72, v70
	v_or_b32_e32 v150, s25, v70
	s_waitcnt lgkmcnt(0)
	v_mul_f32_e32 v66, v74, v66
	v_lshlrev_b64 v[70:71], 11, v[150:151]
	v_cvt_pk_bf16_f32 v66, v66, s0
	v_lshl_add_u64 v[70:71], v[134:135], 0, v[70:71]
	v_mul_f32_e32 v67, v75, v67
	global_store_short v[70:71], v66, off
	v_or_b32_e32 v66, 17, v137
	v_cvt_pk_bf16_f32 v70, v67, s0
	v_bitop3_b32 v67, v136, 46, 4 bitop3:0x6c
	v_cndmask_b32_e64 v66, v67, v66, s[20:21]
	v_or_b32_e32 v66, s72, v66
	v_or_b32_e32 v150, s25, v66
	v_lshlrev_b64 v[66:67], 11, v[150:151]
	v_lshl_add_u64 v[66:67], v[134:135], 0, v[66:67]
	global_store_short v[66:67], v70, off
	v_mul_f32_e32 v67, v76, v68
	v_or_b32_e32 v66, 18, v137
	v_cvt_pk_bf16_f32 v68, v67, s0
	v_bitop3_b32 v67, v136, 45, 4 bitop3:0x6c
	v_cndmask_b32_e64 v66, v67, v66, s[20:21]
	v_or_b32_e32 v66, s72, v66
	v_or_b32_e32 v150, s25, v66
	v_lshlrev_b64 v[66:67], 11, v[150:151]
	v_lshl_add_u64 v[66:67], v[134:135], 0, v[66:67]
	global_store_short v[66:67], v68, off
	v_mul_f32_e32 v67, v77, v69
	v_or_b32_e32 v66, 19, v137
	v_cvt_pk_bf16_f32 v68, v67, s0
	v_bitop3_b32 v67, v136, 44, 4 bitop3:0x6c
	v_cndmask_b32_e64 v66, v67, v66, s[20:21]
	v_or_b32_e32 v66, s72, v66
	v_or_b32_e32 v150, s25, v66
	v_lshlrev_b64 v[66:67], 11, v[150:151]
	v_lshl_add_u64 v[66:67], v[134:135], 0, v[66:67]
	global_store_short v[66:67], v68, off
	ds_read_b128 v[66:69], v138 offset:96
	v_or_b32_e32 v70, 24, v137
	v_bitop3_b32 v71, v136, 39, 4 bitop3:0x6c
	v_cndmask_b32_e64 v70, v71, v70, s[20:21]
	v_or_b32_e32 v70, s72, v70
	v_or_b32_e32 v150, s25, v70
	s_waitcnt lgkmcnt(0)
	v_mul_f32_e32 v66, v78, v66
	v_lshlrev_b64 v[70:71], 11, v[150:151]
	v_cvt_pk_bf16_f32 v66, v66, s0
	v_lshl_add_u64 v[70:71], v[134:135], 0, v[70:71]
	v_mul_f32_e32 v67, v79, v67
	global_store_short v[70:71], v66, off
	v_or_b32_e32 v66, 25, v137
	v_cvt_pk_bf16_f32 v70, v67, s0
	v_bitop3_b32 v67, v136, 38, 4 bitop3:0x6c
	v_cndmask_b32_e64 v66, v67, v66, s[20:21]
	v_or_b32_e32 v66, s72, v66
	v_or_b32_e32 v150, s25, v66
	v_lshlrev_b64 v[66:67], 11, v[150:151]
	v_lshl_add_u64 v[66:67], v[134:135], 0, v[66:67]
	global_store_short v[66:67], v70, off
	v_mul_f32_e32 v67, v80, v68
	v_or_b32_e32 v66, 26, v137
	v_cvt_pk_bf16_f32 v68, v67, s0
	v_bitop3_b32 v67, v136, 37, 4 bitop3:0x6c
	v_cndmask_b32_e64 v66, v67, v66, s[20:21]
	v_or_b32_e32 v66, s72, v66
	v_or_b32_e32 v150, s25, v66
	v_lshlrev_b64 v[66:67], 11, v[150:151]
	v_lshl_add_u64 v[66:67], v[134:135], 0, v[66:67]
	global_store_short v[66:67], v68, off
	v_mul_f32_e32 v67, v81, v69
	v_or_b32_e32 v66, 27, v137
	v_cvt_pk_bf16_f32 v68, v67, s0
	v_bitop3_b32 v67, v136, 36, 4 bitop3:0x6c
	v_cndmask_b32_e64 v66, v67, v66, s[20:21]
	v_or_b32_e32 v66, s72, v66
	v_or_b32_e32 v150, s25, v66
	v_lshlrev_b64 v[66:67], 11, v[150:151]
	v_lshl_add_u64 v[66:67], v[134:135], 0, v[66:67]
	global_store_short v[66:67], v68, off
	ds_read_b128 v[66:69], v138 offset:128
	v_or_b32_e32 v70, 32, v137
	v_bitop3_b32 v71, v136, 31, 4 bitop3:0x6c
	v_cndmask_b32_e64 v70, v71, v70, s[20:21]
	v_or_b32_e32 v70, s72, v70
	v_or_b32_e32 v150, s25, v70
	s_waitcnt lgkmcnt(0)
	v_mul_f32_e32 v66, v82, v66
	v_lshlrev_b64 v[70:71], 11, v[150:151]
	v_cvt_pk_bf16_f32 v66, v66, s0
	v_lshl_add_u64 v[70:71], v[134:135], 0, v[70:71]
	v_mul_f32_e32 v67, v83, v67
	global_store_short v[70:71], v66, off
	v_or_b32_e32 v66, 33, v137
	v_cvt_pk_bf16_f32 v70, v67, s0
	v_bitop3_b32 v67, v136, 30, 4 bitop3:0x6c
	v_cndmask_b32_e64 v66, v67, v66, s[20:21]
	v_or_b32_e32 v66, s72, v66
	v_or_b32_e32 v150, s25, v66
	v_lshlrev_b64 v[66:67], 11, v[150:151]
	v_lshl_add_u64 v[66:67], v[134:135], 0, v[66:67]
	global_store_short v[66:67], v70, off
	v_mul_f32_e32 v67, v84, v68
	v_or_b32_e32 v66, 34, v137
	v_cvt_pk_bf16_f32 v68, v67, s0
	v_bitop3_b32 v67, v136, 29, 4 bitop3:0x6c
	v_cndmask_b32_e64 v66, v67, v66, s[20:21]
	v_or_b32_e32 v66, s72, v66
	v_or_b32_e32 v150, s25, v66
	v_lshlrev_b64 v[66:67], 11, v[150:151]
	v_lshl_add_u64 v[66:67], v[134:135], 0, v[66:67]
	global_store_short v[66:67], v68, off
	v_mul_f32_e32 v67, v85, v69
	v_or_b32_e32 v66, 35, v137
	v_cvt_pk_bf16_f32 v68, v67, s0
	v_bitop3_b32 v67, v136, 28, 4 bitop3:0x6c
	v_cndmask_b32_e64 v66, v67, v66, s[20:21]
	v_or_b32_e32 v66, s72, v66
	v_or_b32_e32 v150, s25, v66
	v_lshlrev_b64 v[66:67], 11, v[150:151]
	v_lshl_add_u64 v[66:67], v[134:135], 0, v[66:67]
	global_store_short v[66:67], v68, off
	ds_read_b128 v[66:69], v138 offset:160
	v_or_b32_e32 v70, 40, v137
	v_bitop3_b32 v71, v136, 23, 4 bitop3:0x6c
	v_cndmask_b32_e64 v70, v71, v70, s[20:21]
	v_or_b32_e32 v70, s72, v70
	v_or_b32_e32 v150, s25, v70
	s_waitcnt lgkmcnt(0)
	v_mul_f32_e32 v66, v86, v66
	v_lshlrev_b64 v[70:71], 11, v[150:151]
	v_cvt_pk_bf16_f32 v66, v66, s0
	v_lshl_add_u64 v[70:71], v[134:135], 0, v[70:71]
	v_mul_f32_e32 v67, v87, v67
	global_store_short v[70:71], v66, off
	v_or_b32_e32 v66, 41, v137
	v_cvt_pk_bf16_f32 v70, v67, s0
	v_bitop3_b32 v67, v136, 22, 4 bitop3:0x6c
	v_cndmask_b32_e64 v66, v67, v66, s[20:21]
	v_or_b32_e32 v66, s72, v66
	v_or_b32_e32 v150, s25, v66
	v_lshlrev_b64 v[66:67], 11, v[150:151]
	v_lshl_add_u64 v[66:67], v[134:135], 0, v[66:67]
	global_store_short v[66:67], v70, off
	v_mul_f32_e32 v67, v88, v68
	v_or_b32_e32 v66, 42, v137
	v_cvt_pk_bf16_f32 v68, v67, s0
	v_bitop3_b32 v67, v136, 21, 4 bitop3:0x6c
	v_cndmask_b32_e64 v66, v67, v66, s[20:21]
	v_or_b32_e32 v66, s72, v66
	v_or_b32_e32 v150, s25, v66
	v_lshlrev_b64 v[66:67], 11, v[150:151]
	v_lshl_add_u64 v[66:67], v[134:135], 0, v[66:67]
	global_store_short v[66:67], v68, off
	v_mul_f32_e32 v67, v89, v69
	v_or_b32_e32 v66, 43, v137
	v_cvt_pk_bf16_f32 v68, v67, s0
	v_bitop3_b32 v67, v136, 20, 4 bitop3:0x6c
	v_cndmask_b32_e64 v66, v67, v66, s[20:21]
	v_or_b32_e32 v66, s72, v66
	v_or_b32_e32 v150, s25, v66
	v_lshlrev_b64 v[66:67], 11, v[150:151]
	v_lshl_add_u64 v[66:67], v[134:135], 0, v[66:67]
	global_store_short v[66:67], v68, off
	ds_read_b128 v[66:69], v138 offset:192
	v_or_b32_e32 v70, 48, v137
	v_bitop3_b32 v71, v136, 15, 4 bitop3:0x6c
	v_cndmask_b32_e64 v70, v71, v70, s[20:21]
	v_or_b32_e32 v70, s72, v70
	v_or_b32_e32 v150, s25, v70
	s_waitcnt lgkmcnt(0)
	v_mul_f32_e32 v66, v90, v66
	v_lshlrev_b64 v[70:71], 11, v[150:151]
	v_cvt_pk_bf16_f32 v66, v66, s0
	v_lshl_add_u64 v[70:71], v[134:135], 0, v[70:71]
	v_mul_f32_e32 v67, v91, v67
	global_store_short v[70:71], v66, off
	v_or_b32_e32 v66, 49, v137
	v_cvt_pk_bf16_f32 v70, v67, s0
	v_bitop3_b32 v67, v136, 14, 4 bitop3:0x6c
	v_cndmask_b32_e64 v66, v67, v66, s[20:21]
	v_or_b32_e32 v66, s72, v66
	v_or_b32_e32 v150, s25, v66
	v_lshlrev_b64 v[66:67], 11, v[150:151]
	v_lshl_add_u64 v[66:67], v[134:135], 0, v[66:67]
	global_store_short v[66:67], v70, off
	v_mul_f32_e32 v67, v92, v68
	v_or_b32_e32 v66, 50, v137
	v_cvt_pk_bf16_f32 v68, v67, s0
	v_bitop3_b32 v67, v136, 13, 4 bitop3:0x6c
	v_cndmask_b32_e64 v66, v67, v66, s[20:21]
	v_or_b32_e32 v66, s72, v66
	v_or_b32_e32 v150, s25, v66
	v_lshlrev_b64 v[66:67], 11, v[150:151]
	v_lshl_add_u64 v[66:67], v[134:135], 0, v[66:67]
	global_store_short v[66:67], v68, off
	v_mul_f32_e32 v67, v93, v69
	v_or_b32_e32 v66, 51, v137
	v_cvt_pk_bf16_f32 v68, v67, s0
	v_bitop3_b32 v67, v136, 12, 4 bitop3:0x6c
	v_cndmask_b32_e64 v66, v67, v66, s[20:21]
	v_or_b32_e32 v66, s72, v66
	v_or_b32_e32 v150, s25, v66
	v_lshlrev_b64 v[66:67], 11, v[150:151]
	v_lshl_add_u64 v[66:67], v[134:135], 0, v[66:67]
	global_store_short v[66:67], v68, off
	ds_read_b128 v[66:69], v138 offset:224
	v_or_b32_e32 v70, 56, v137
	v_bitop3_b32 v71, v136, 7, 4 bitop3:0x6c
	v_cndmask_b32_e64 v70, v71, v70, s[20:21]
	v_or_b32_e32 v70, s72, v70
	v_or_b32_e32 v150, s25, v70
	s_waitcnt lgkmcnt(0)
	v_mul_f32_e32 v66, v94, v66
	v_lshlrev_b64 v[70:71], 11, v[150:151]
	v_cvt_pk_bf16_f32 v66, v66, s0
	v_lshl_add_u64 v[70:71], v[134:135], 0, v[70:71]
	v_mul_f32_e32 v67, v95, v67
	global_store_short v[70:71], v66, off
	v_or_b32_e32 v66, 57, v137
	v_cvt_pk_bf16_f32 v70, v67, s0
	v_bitop3_b32 v67, v136, 6, 4 bitop3:0x6c
	v_cndmask_b32_e64 v66, v67, v66, s[20:21]
	v_or_b32_e32 v66, s72, v66
	v_or_b32_e32 v150, s25, v66
	v_lshlrev_b64 v[66:67], 11, v[150:151]
	v_lshl_add_u64 v[66:67], v[134:135], 0, v[66:67]
	global_store_short v[66:67], v70, off
	v_mul_f32_e32 v67, v96, v68
	v_or_b32_e32 v66, 58, v137
	v_cvt_pk_bf16_f32 v68, v67, s0
	v_bitop3_b32 v67, v136, 5, 4 bitop3:0x6c
	v_cndmask_b32_e64 v66, v67, v66, s[20:21]
	v_or_b32_e32 v66, s72, v66
	v_or_b32_e32 v150, s25, v66
	v_lshlrev_b64 v[66:67], 11, v[150:151]
	v_lshl_add_u64 v[66:67], v[134:135], 0, v[66:67]
	global_store_short v[66:67], v68, off
	v_mul_f32_e32 v67, v97, v69
	v_or_b32_e32 v66, 59, v137
	v_cvt_pk_bf16_f32 v68, v67, s0
	v_bitop3_b32 v67, v136, 4, v136 bitop3:0xc
	v_cndmask_b32_e64 v66, v67, v66, s[20:21]
	v_or_b32_e32 v66, s72, v66
	v_or_b32_e32 v150, s25, v66
	v_lshlrev_b64 v[66:67], 11, v[150:151]
	v_lshl_add_u64 v[66:67], v[134:135], 0, v[66:67]
	v_add_f32_e32 v155, v153, v139
	s_cmpk_eq_i32 s77, 0x2000
	s_mov_b32 s80, s78
	global_store_short v[66:67], v68, off
	s_cbranch_scc1 .LBB0_346
.LBB0_356:
	s_add_i32 s79, s77, 0
	s_add_i32 s0, s79, 0x1c0fc
	v_mov_b32_e32 v72, v156
	v_mov_b32_e32 v66, s0
	ds_read_b32 v67, v66
	v_and_b32_e32 v66, 15, v72
	v_lshlrev_b32_e32 v73, 4, v66
	v_ashrrev_i32_e32 v66, 4, v72
	v_and_b32_e32 v74, 0x70, v72
	v_lshlrev_b32_e32 v68, 8, v66
	v_bitop3_b32 v68, v73, v68, v74 bitop3:0xde
	v_add_u32_e32 v68, 0, v68
	s_waitcnt vmcnt(32)
	ds_write_b128 v68, v[98:101]
	ds_write_b128 v68, v[102:105] offset:16384
	v_lshl_add_u32 v68, v66, 2, s79
	v_add_u32_e32 v68, 0x1a000, v68
	ds_read_b32 v68, v68
	s_waitcnt lgkmcnt(0)
	v_max_f32_e32 v67, v67, v67
	v_max_f32_e32 v185, v155, v155
	v_max_f32_e32 v153, v185, v67
	v_and_b32_e32 v69, 0xffff0000, v102
	s_waitcnt lgkmcnt(0)
	v_sub_f32_e32 v67, v68, v153
	v_mul_f32_e32 v67, 0x3fb8aa3b, v67
	v_exp_f32_e32 v67, v67
	v_lshlrev_b32_e32 v68, 16, v102
	v_and_b32_e32 v70, 0xffff0000, v103
	v_and_b32_e32 v71, 0xffff0000, v104
	v_mul_f32_e32 v68, v67, v68
	v_mul_f32_e32 v69, v67, v69
	v_cvt_pk_bf16_f32 v68, v68, v69
	v_lshlrev_b32_e32 v69, 16, v103
	v_mul_f32_e32 v69, v67, v69
	v_mul_f32_e32 v70, v67, v70
	v_cvt_pk_bf16_f32 v69, v69, v70
	v_lshlrev_b32_e32 v70, 16, v104
	v_mul_f32_e32 v70, v67, v70
	v_mul_f32_e32 v71, v67, v71
	v_cvt_pk_bf16_f32 v70, v70, v71
	v_lshlrev_b32_e32 v71, 16, v105
	v_and_b32_e32 v77, 0xffff0000, v105
	v_mul_f32_e32 v71, v67, v71
	v_mul_f32_e32 v67, v67, v77
	v_cvt_pk_bf16_f32 v71, v71, v67
	v_and_b32_e32 v67, 0xfffff0, v66
	v_lshlrev_b32_e32 v77, 1, v66
	v_and_or_b32 v67, v77, 8, v67
	v_bfe_u32 v75, v72, 2, 2
	v_lshrrev_b32_e32 v77, 1, v66
	v_lshrrev_b32_e32 v67, 1, v67
	v_and_b32_e32 v78, 3, v66
	v_or_b32_e32 v67, v67, v75
	v_and_or_b32 v77, v77, 4, v78
	v_and_b32_e32 v76, 48, v73
	v_lshlrev_b32_e32 v77, 6, v77
	v_lshl_add_u32 v67, v67, 9, 0
	v_add3_u32 v67, v67, v77, v76
	v_add_u32_e32 v77, 0x200, v72
	ds_write_b128 v67, v[68:71] offset:32768
	v_ashrrev_i32_e32 v67, 4, v77
	v_lshlrev_b32_e32 v68, 8, v67
	v_bitop3_b32 v68, v68, v73, v74 bitop3:0xf6
	v_add_u32_e32 v68, 0, v68
	ds_write_b128 v68, v[106:109]
	ds_write_b128 v68, v[110:113] offset:16384
	v_lshl_add_u32 v68, v67, 2, s79
	v_add_u32_e32 v68, 0x1a000, v68
	ds_read_b32 v68, v68
	v_and_b32_e32 v69, 0xffff0000, v110
	v_and_b32_e32 v70, 0xffff0000, v111
	v_and_b32_e32 v73, 0xffff0000, v112
	v_and_b32_e32 v74, 0xffff0000, v113
	s_waitcnt lgkmcnt(0)
	v_sub_f32_e32 v68, v68, v153
	v_mul_f32_e32 v68, 0x3fb8aa3b, v68
	v_exp_f32_e32 v71, v68
	v_lshlrev_b32_e32 v68, 16, v110
	s_add_i32 s78, s80, 1
	s_cmpk_eq_i32 s77, 0x1f00
	v_mul_f32_e32 v68, v71, v68
	v_mul_f32_e32 v69, v71, v69
	v_cvt_pk_bf16_f32 v68, v68, v69
	v_lshlrev_b32_e32 v69, 16, v111
	v_mul_f32_e32 v69, v71, v69
	v_mul_f32_e32 v70, v71, v70
	v_cvt_pk_bf16_f32 v69, v69, v70
	v_lshlrev_b32_e32 v70, 16, v112
	v_mul_f32_e32 v70, v71, v70
	v_mul_f32_e32 v73, v71, v73
	v_cvt_pk_bf16_f32 v70, v70, v73
	v_lshlrev_b32_e32 v73, 16, v113
	v_mul_f32_e32 v73, v71, v73
	v_mul_f32_e32 v71, v71, v74
	v_cvt_pk_bf16_f32 v71, v73, v71
	v_and_b32_e32 v73, 0xfffff0, v67
	v_lshlrev_b32_e32 v74, 1, v67
	v_and_or_b32 v73, v74, 8, v73
	v_lshrrev_b32_e32 v73, 1, v73
	v_lshrrev_b32_e32 v74, 1, v67
	v_or_b32_e32 v73, v73, v75
	v_and_b32_e32 v75, 3, v67
	v_and_or_b32 v74, v74, 4, v75
	v_lshlrev_b32_e32 v74, 6, v74
	v_lshl_add_u32 v73, v73, 9, 0
	v_add3_u32 v73, v73, v74, v76
	ds_write_b128 v73, v[68:71] offset:32768
	v_lshlrev_b32_e32 v69, 4, v72
	v_lshlrev_b32_e32 v68, 10, v72
	v_and_b32_e32 v75, 48, v69
	v_ashrrev_i32_e32 v69, 5, v72
	v_and_b32_e32 v68, 0x4000, v68
	v_and_b32_e32 v70, 0xfffff0, v69
	v_lshlrev_b32_e32 v71, 1, v69
	v_add_u32_e32 v73, 0, v68
	v_lshlrev_b32_e32 v68, 3, v72
	v_and_or_b32 v70, v71, 8, v70
	v_bfe_u32 v74, v68, 5, 2
	v_lshrrev_b32_e32 v71, 1, v69
	v_lshrrev_b32_e32 v70, 1, v70
	v_and_b32_e32 v76, 3, v69
	v_or_b32_e32 v70, v70, v74
	v_and_or_b32 v71, v71, 4, v76
	v_lshlrev_b32_e32 v71, 6, v71
	v_lshl_add_u32 v70, v70, 9, v73
	v_add3_u32 v70, v70, v71, v75
	ds_write_b128 v70, v[114:117] offset:49152
	v_ashrrev_i32_e32 v70, 5, v77
	v_and_b32_e32 v71, 0xfffff0, v70
	v_lshlrev_b32_e32 v76, 1, v70
	v_and_or_b32 v71, v76, 8, v71
	v_lshrrev_b32_e32 v76, 1, v70
	v_lshrrev_b32_e32 v71, 1, v71
	v_and_b32_e32 v77, 3, v70
	v_or_b32_e32 v71, v71, v74
	v_and_or_b32 v76, v76, 4, v77
	v_lshlrev_b32_e32 v76, 6, v76
	v_lshl_add_u32 v71, v71, 9, v73
	v_add3_u32 v71, v71, v76, v75
	ds_write_b128 v71, v[118:121] offset:49152
	v_add_u32_e32 v71, 0x400, v72
	v_ashrrev_i32_e32 v71, 5, v71
	v_and_b32_e32 v76, 0xfffff0, v71
	v_lshlrev_b32_e32 v77, 1, v71
	v_and_or_b32 v76, v77, 8, v76
	v_lshrrev_b32_e32 v77, 1, v71
	v_lshrrev_b32_e32 v76, 1, v76
	v_and_b32_e32 v78, 3, v71
	v_or_b32_e32 v76, v76, v74
	v_and_or_b32 v77, v77, 4, v78
	v_lshlrev_b32_e32 v77, 6, v77
	v_lshl_add_u32 v76, v76, 9, v73
	v_add_u32_e32 v72, 0x600, v72
	v_add3_u32 v76, v76, v77, v75
	v_ashrrev_i32_e32 v72, 5, v72
	ds_write_b128 v76, v[122:125] offset:49152
	v_and_b32_e32 v76, 0xfffff0, v72
	v_lshlrev_b32_e32 v77, 1, v72
	v_and_or_b32 v76, v77, 8, v76
	v_lshrrev_b32_e32 v76, 1, v76
	v_lshrrev_b32_e32 v77, 1, v72
	v_or_b32_e32 v74, v76, v74
	v_and_b32_e32 v76, 3, v72
	v_and_or_b32 v76, v77, 4, v76
	v_lshlrev_b32_e32 v76, 6, v76
	v_lshl_add_u32 v73, v74, 9, v73
	v_add3_u32 v73, v73, v76, v75
	ds_write_b128 v73, v[126:129] offset:49152
	s_cbranch_scc1 .LBB0_358
	s_and_b64 s[0:1], s[20:21], exec
	s_cselect_b32 s0, s78, s76
	s_lshl_b32 s0, s0, 6
	v_sub_u32_e32 v74, 63, v66
	v_cndmask_b32_e64 v66, v74, v66, s[20:21]
	s_add_i32 s25, s0, s72
	v_add_u32_e32 v66, s25, v66
	v_mov_b64_e32 v[74:75], s[34:35]
	v_mad_i64_i32 v[76:77], s[0:1], v66, s57, v[74:75]
	v_sub_u32_e32 v66, 63, v67
	v_cndmask_b32_e64 v66, v66, v67, s[20:21]
	v_and_b32_e32 v73, 0x78, v68
	v_add_u32_e32 v66, s25, v66
	v_lshlrev_b32_e32 v150, 1, v73
	v_mad_i64_i32 v[66:67], s[0:1], v66, s57, v[74:75]
	v_lshl_add_u64 v[76:77], v[76:77], 0, v[150:151]
	v_lshl_add_u64 v[66:67], v[66:67], 0, v[150:151]
	global_load_dwordx4 v[98:101], v[76:77], off
	global_load_dwordx4 v[102:105], v[76:77], off offset:1024
	global_load_dwordx4 v[106:109], v[66:67], off
	global_load_dwordx4 v[110:113], v[66:67], off offset:1024
	v_sub_u32_e32 v66, 63, v69
	v_cndmask_b32_e64 v66, v66, v69, s[20:21]
	v_sub_u32_e32 v73, 63, v70
	v_add_u32_e32 v69, s25, v66
	v_mov_b64_e32 v[66:67], s[36:37]
	v_and_b32_e32 v68, 0xf8, v68
	v_cndmask_b32_e64 v70, v73, v70, s[20:21]
	v_mad_i64_i32 v[74:75], s[0:1], v69, s57, v[66:67]
	v_lshlrev_b32_e32 v150, 1, v68
	v_add_u32_e32 v70, s25, v70
	v_lshl_add_u64 v[68:69], v[74:75], 0, v[150:151]
	v_mad_i64_i32 v[74:75], s[0:1], v70, s57, v[66:67]
	v_lshl_add_u64 v[74:75], v[74:75], 0, v[150:151]
	global_load_dwordx4 v[114:117], v[68:69], off offset:2048
	global_load_dwordx4 v[118:121], v[74:75], off offset:2048
	v_sub_u32_e32 v68, 63, v71
	v_cndmask_b32_e64 v68, v68, v71, s[20:21]
	v_sub_u32_e32 v70, 63, v72
	v_add_u32_e32 v68, s25, v68
	v_cndmask_b32_e64 v70, v70, v72, s[20:21]
	v_mad_i64_i32 v[68:69], s[0:1], v68, s57, v[66:67]
	v_add_u32_e32 v70, s25, v70
	v_lshl_add_u64 v[68:69], v[68:69], 0, v[150:151]
	v_mad_i64_i32 v[66:67], s[0:1], v70, s57, v[66:67]
	v_lshl_add_u64 v[66:67], v[66:67], 0, v[150:151]
	global_load_dwordx4 v[122:125], v[68:69], off offset:2048
	global_load_dwordx4 v[126:129], v[66:67], off offset:2048

.LBB0_961:
	s_ashr_i32 s14, s46, 7
	s_and_b32 s28, s46, 3
	s_ashr_i32 s15, s14, 31
	s_lshl_b32 s0, s28, 7
	s_lshl_b64 s[12:13], s[14:15], 15
	v_or_b32_e32 v14, s0, v171
	s_waitcnt lgkmcnt(0)
	s_add_u32 s12, s16, s12
	s_addc_u32 s13, s17, s13
	v_lshlrev_b32_e32 v84, 2, v14
	v_lshl_add_u64 v[2:3], s[12:13], 0, v[84:85]
	v_lshl_add_u64 v[2:3], v[2:3], 0, v[156:157]
	s_movk_i32 s1, 0x1000
	v_add_co_u32_e32 v10, vcc, s1, v2
	s_movk_i32 s1, 0x2000
	s_nop 0
	v_addc_co_u32_e32 v11, vcc, 0, v3, vcc
	v_add_co_u32_e32 v6, vcc, s1, v2
	s_movk_i32 s1, 0x3000
	s_nop 0
	v_addc_co_u32_e32 v7, vcc, 0, v3, vcc
	v_add_co_u32_e32 v12, vcc, s1, v2
	s_cmpk_lt_u32 s46, 0x80
	global_load_dword v4, v[6:7], off offset:-4096
	global_load_dword v5, v[6:7], off
	s_nop 0
	global_load_dword v6, v[6:7], off offset:2048
	v_addc_co_u32_e32 v13, vcc, 0, v3, vcc
	global_load_dword v7, v[2:3], off
	global_load_dword v8, v[2:3], off offset:2048
	global_load_dword v9, v[10:11], off offset:2048
	s_nop 0
	global_load_dword v10, v[12:13], off
	global_load_dword v11, v[12:13], off offset:2048
	v_lshl_or_b32 v2, s14, 9, v14
	s_cselect_b64 s[12:13], -1, 0
	v_ashrrev_i32_e32 v3, 31, v2
	s_and_b64 s[26:27], s[12:13], exec
	v_lshl_add_u64 v[2:3], v[2:3], 2, s[18:19]
	s_cselect_b32 s1, 0, 0x7e0
	s_lshl_b32 s20, s46, 9
	global_load_dword v180, v[2:3], off
	v_cndmask_b32_e64 v2, v173, v172, s[12:13]
	s_and_b32 s47, s20, 0xf800
	v_add_u32_e32 v15, s47, v2
	v_add_u32_e32 v2, s1, v15
	v_mad_i64_i32 v[2:3], s[26:27], v2, s39, v[160:161]
	s_lshl_b32 s20, s28, 8
	v_lshl_add_u64 v[2:3], v[2:3], 0, s[20:21]
	v_lshl_add_u64 v[2:3], v[2:3], 0, v[164:165]
	s_waitcnt vmcnt(0)
	global_load_dwordx4 v[88:91], v[2:3], off
	global_load_dwordx4 v[92:95], v[2:3], off offset:1024
	v_cndmask_b32_e64 v2, v175, v174, s[12:13]
	v_add_u32_e32 v13, s47, v2
	v_add_u32_e32 v2, s1, v13
	v_cndmask_b32_e64 v12, v177, v176, s[12:13]
	v_mad_i64_i32 v[2:3], s[26:27], v2, s39, v[160:161]
	v_add_u32_e32 v14, s47, v12
	s_lshl_b32 s26, s28, 9
	s_mov_b32 s27, s21
	v_add_u32_e32 v12, s1, v14
	v_lshl_add_u64 v[2:3], v[2:3], 0, s[26:27]
	v_mad_i64_i32 v[16:17], s[28:29], v12, s39, v[160:161]
	v_lshl_add_u64 v[2:3], v[2:3], 0, v[168:169]
	v_lshl_add_u64 v[16:17], v[16:17], 0, s[26:27]
	v_lshl_add_u64 v[16:17], v[16:17], 0, v[168:169]
	global_load_dwordx4 v[96:99], v[2:3], off offset:2048
	global_load_dwordx4 v[100:103], v[16:17], off offset:2048
	v_mov_b32_e32 v86, v85
	v_mov_b32_e32 v87, v85
	v_mov_b32_e32 v84, v85
	v_cndmask_b32_e64 v2, v178, v170, s[12:13]
	v_mov_b64_e32 v[106:107], v[86:87]
	v_mov_b64_e32 v[110:111], v[86:87]
	s_and_b64 vcc, exec, s[8:9]
	v_or_b32_e32 v12, s47, v2
	v_lshlrev_b32_e32 v2, 2, v158
	v_mov_b64_e32 v[104:105], v[84:85]
	v_mov_b64_e32 v[108:109], v[84:85]
	s_cbranch_vccnz .LBB0_963
	v_or_b32_e32 v3, s1, v12
	v_lshlrev_b32_e32 v84, 7, v3
	s_lshl_b32 s26, s14, 4
	v_lshl_add_u64 v[16:17], s[24:25], 0, v[84:85]
	s_ashr_i32 s27, s26, 31
	v_lshl_add_u64 v[16:17], s[26:27], 2, v[16:17]
	v_mov_b32_e32 v3, v85
	v_lshl_add_u64 v[16:17], v[16:17], 0, v[2:3]
	global_load_dwordx4 v[104:107], v[16:17], off
	global_load_dwordx4 v[108:111], v[16:17], off offset:16
.LBB0_963:
	s_and_b64 s[26:27], s[12:13], exec
	s_cselect_b32 s1, 32, 0x7c0
	v_add_u32_e32 v3, s1, v15
	v_mov_b64_e32 v[16:17], s[22:23]
	v_mad_i64_i32 v[18:19], s[26:27], v3, s39, v[16:17]
	s_lshl_b32 s30, s0, 1
	s_mov_b32 s31, s21
	v_lshl_add_u64 v[18:19], v[18:19], 0, s[30:31]
	v_mov_b32_e32 v163, v85
	v_lshl_add_u64 v[18:19], v[18:19], 0, v[162:163]
	v_add_u32_e32 v3, s1, v13
	global_load_dwordx4 v[112:115], v[18:19], off
	global_load_dwordx4 v[116:119], v[18:19], off offset:1024
	v_mad_i64_i32 v[18:19], s[26:27], v3, s39, v[16:17]
	s_lshl_b32 s20, s20, 1
	v_add_u32_e32 v3, s1, v14
	v_lshl_add_u64 v[18:19], v[18:19], 0, s[20:21]
	v_mov_b32_e32 v167, v85
	v_mad_i64_i32 v[14:15], s[26:27], v3, s39, v[16:17]
	v_lshl_add_u64 v[18:19], v[18:19], 0, v[166:167]
	v_lshl_add_u64 v[14:15], v[14:15], 0, s[20:21]
	v_lshl_add_u64 v[14:15], v[14:15], 0, v[166:167]
	global_load_dwordx4 v[120:123], v[18:19], off offset:2048
	global_load_dwordx4 v[124:127], v[14:15], off offset:2048
	s_andn2_b64 vcc, exec, s[64:65]
	s_mov_b64 s[28:29], -1
	s_cbranch_vccnz .LBB0_965
	s_lshl_b32 s26, s14, 4
	s_ashr_i32 s27, s26, 31
	s_mov_b64 s[28:29], 0
.LBB0_965:
	s_andn2_b64 vcc, exec, s[28:29]
	s_cbranch_vccnz .LBB0_967
	v_or_b32_e32 v3, s1, v12
	v_lshlrev_b32_e32 v84, 7, v3
	s_lshl_b32 s26, s14, 4
	v_lshl_add_u64 v[12:13], s[24:25], 0, v[84:85]
	s_ashr_i32 s27, s26, 31
	v_lshl_add_u64 v[12:13], s[26:27], 2, v[12:13]
	v_mov_b32_e32 v3, v85
	v_lshl_add_u64 v[2:3], v[12:13], 0, v[2:3]
	global_load_dwordx4 v[132:135], v[2:3], off
	global_load_dwordx4 v[136:139], v[2:3], off offset:16
	s_branch .LBB0_968

.LBB0_969:
	v_mov_b32_e32 v86, v159
	s_waitcnt lgkmcnt(0)
	s_barrier
	v_cvt_pk_bf16_f32 v194, v58, v59
	v_and_b32_e32 v84, 31, v86
	v_bfe_u32 v192, v86, 5, 1
	v_lshlrev_b32_e32 v87, 4, v86
	v_lshlrev_b32_e32 v200, 4, v192
	v_lshlrev_b32_e32 v193, 8, v84
	v_and_b32_e32 v201, 0x70, v87
	v_bitop3_b32 v66, v201, v193, v200 bitop3:0xde
	v_add_u32_e32 v70, 0, v66
	ds_read_b128 v[66:69], v70 offset:8192
	ds_read_b128 v[70:73], v70
	s_waitcnt lgkmcnt(0)
	v_mfma_f32_32x32x16_bf16 v[68:83], v[66:69], v[70:73], 0
	v_or_b32_e32 v66, 32, v200
	v_bitop3_b32 v66, v66, v193, v201 bitop3:0xde
	v_add_u32_e32 v66, 0, v66
	ds_read_b128 v[140:143], v66 offset:8192
	ds_read_b128 v[144:147], v66
	v_or_b32_e32 v66, 64, v200
	v_bitop3_b32 v66, v66, v193, v201 bitop3:0xde
	v_add_u32_e32 v66, 0, v66
	s_waitcnt lgkmcnt(0)
	v_mfma_f32_32x32x16_bf16 v[68:83], v[140:143], v[144:147], v[68:83]
	ds_read_b128 v[140:143], v66 offset:8192
	ds_read_b128 v[144:147], v66
	v_or_b32_e32 v66, 0x60, v200
	v_bitop3_b32 v66, v66, v193, v201 bitop3:0xde
	v_add_u32_e32 v66, 0, v66
	ds_read_b128 v[148:151], v66 offset:8192
	v_and_b32_e32 v67, 63, v86
	v_lshlrev_b32_e32 v86, 1, v86
	s_waitcnt lgkmcnt(0)
	v_mfma_f32_32x32x16_bf16 v[68:83], v[140:143], v[144:147], v[68:83]
	ds_read_b128 v[140:143], v66
	v_or_b32_e32 v66, 0x80, v200
	v_bitop3_b32 v66, v66, v193, v201 bitop3:0xde
	v_add_u32_e32 v66, 0, v66
	ds_read_b128 v[144:147], v66 offset:8192
	v_lshlrev_b32_e32 v67, 3, v67
	v_and_b32_e32 v87, 0xc0, v87
	s_waitcnt lgkmcnt(0)
	v_mfma_f32_32x32x16_bf16 v[68:83], v[148:151], v[140:143], v[68:83]
	ds_read_b128 v[140:143], v66
	v_or_b32_e32 v66, 0xa0, v200
	v_bitop3_b32 v66, v66, v193, v201 bitop3:0xde
	v_add_u32_e32 v66, 0, v66
	ds_read_b128 v[148:151], v66 offset:8192
	v_and_b32_e32 v152, 32, v86
	v_lshlrev_b32_e32 v86, 2, v192
	s_waitcnt lgkmcnt(0)
	v_mfma_f32_32x32x16_bf16 v[68:83], v[144:147], v[140:143], v[68:83]
	ds_read_b128 v[140:143], v66
	v_or_b32_e32 v66, 0xc0, v200
	v_bitop3_b32 v66, v66, v193, v201 bitop3:0xde
	v_add_u32_e32 v66, 0, v66
	ds_read_b128 v[144:147], v66 offset:8192
	v_and_b32_e32 v153, 0x100, v67
	v_and_or_b32 v67, v67, 24, v87
	s_waitcnt lgkmcnt(0)
	v_mfma_f32_32x32x16_bf16 v[68:83], v[148:151], v[140:143], v[68:83]
	ds_read_b128 v[140:143], v66
	v_or_b32_e32 v66, 0xe0, v200
	v_bitop3_b32 v66, v66, v193, v201 bitop3:0xde
	v_add_u32_e32 v66, 0, v66
	ds_read_b128 v[148:151], v66 offset:8192
	v_cmp_le_u32_e32 vcc, v86, v84
	v_or3_b32 v204, v67, v152, v153
	s_waitcnt lgkmcnt(0)
	v_mfma_f32_32x32x16_bf16 v[68:83], v[144:147], v[140:143], v[68:83]
	ds_read_b128 v[140:143], v66
	v_or_b32_e32 v191, 2, v86
	v_or_b32_e32 v190, 3, v86
	v_or_b32_e32 v189, 8, v86
	v_or_b32_e32 v188, 9, v86
	v_or_b32_e32 v187, 10, v86
	v_lshlrev_b32_e32 v203, 3, v192
	s_waitcnt lgkmcnt(0)
	v_mfma_f32_32x32x16_bf16 v[68:83], v[148:151], v[140:143], v[68:83]
	v_add_u32_e32 v205, 0, v193
	v_or_b32_e32 v186, 11, v86
	v_or_b32_e32 v185, 16, v86
	v_or_b32_e32 v184, 17, v86
	v_or_b32_e32 v183, 18, v86
	v_or_b32_e32 v182, 19, v86
	v_or_b32_e32 v181, 24, v86
	s_nop 4
	v_cvt_pk_bf16_f32 v66, v68, s0
	v_cndmask_b32_e32 v66, 0, v66, vcc
	v_cvt_pk_bf16_f32 v67, v69, s0
	v_cmp_lt_u32_e32 vcc, v86, v84
	v_add3_u32 v69, v205, v201, v203
	ds_read2_b64 v[142:145], v69 offset1:16
	v_cndmask_b32_e32 v67, 0, v67, vcc
	v_perm_b32 v152, v67, v66, s45
	v_cvt_pk_bf16_f32 v66, v70, s0
	v_cmp_le_u32_e32 vcc, v191, v84
	v_cvt_pk_bf16_f32 v67, v71, s0
	v_or_b32_e32 v70, 16, v203
	v_cndmask_b32_e32 v66, 0, v66, vcc
	v_cmp_le_u32_e32 vcc, v190, v84
	v_xad_u32 v70, v70, v201, v205
	s_waitcnt lgkmcnt(0)
	v_mov_b32_e32 v71, v143
	v_cndmask_b32_e32 v67, 0, v67, vcc
	v_perm_b32 v153, v67, v66, s45
	v_cvt_pk_bf16_f32 v66, v72, s0
	v_cmp_le_u32_e32 vcc, v189, v84
	v_cvt_pk_bf16_f32 v67, v73, s0
	ds_read_b64 v[72:73], v70
	v_cndmask_b32_e32 v66, 0, v66, vcc
	v_cmp_le_u32_e32 vcc, v188, v84
	v_mov_b32_e32 v70, v142
	v_cvt_pk_bf16_f32 v68, v54, v55
	v_cndmask_b32_e32 v67, 0, v67, vcc
	v_perm_b32 v154, v67, v66, s45
	v_cvt_pk_bf16_f32 v66, v74, s0
	v_cmp_le_u32_e32 vcc, v187, v84
	v_cvt_pk_bf16_f32 v67, v75, s0
	v_or_b32_e32 v74, 32, v203
	v_cndmask_b32_e32 v66, 0, v66, vcc
	v_cmp_le_u32_e32 vcc, v186, v84
	v_or_b32_e32 v75, 48, v203
	v_cvt_pk_bf16_f32 v69, v56, v57
	v_cndmask_b32_e32 v67, 0, v67, vcc
	v_perm_b32 v155, v67, v66, s45
	v_cvt_pk_bf16_f32 v66, v76, s0
	v_cmp_le_u32_e32 vcc, v185, v84
	v_cvt_pk_bf16_f32 v67, v77, s0
	v_or_b32_e32 v76, 64, v203
	v_cndmask_b32_e32 v66, 0, v66, vcc
	v_cmp_le_u32_e32 vcc, v184, v84
	v_xad_u32 v74, v74, v201, v205
	v_xad_u32 v75, v75, v201, v205
	v_cndmask_b32_e32 v67, 0, v67, vcc
	v_perm_b32 v140, v67, v66, s45
	v_cvt_pk_bf16_f32 v66, v78, s0
	v_cmp_le_u32_e32 vcc, v183, v84
	v_cvt_pk_bf16_f32 v67, v79, s0
	v_xad_u32 v76, v76, v201, v205
	v_cndmask_b32_e32 v66, 0, v66, vcc
	v_cmp_le_u32_e32 vcc, v182, v84
	v_cvt_pk_bf16_f32 v151, v81, s0
	ds_read_b64 v[146:147], v74
	ds_read_b64 v[148:149], v75
	ds_read_b64 v[192:193], v76
	v_cndmask_b32_e32 v67, 0, v67, vcc
	v_perm_b32 v141, v67, v66, s45
	v_cvt_pk_bf16_f32 v66, v80, s0
	v_cmp_le_u32_e32 vcc, v181, v84
	v_cvt_pk_bf16_f32 v67, v52, v53
	v_or_b32_e32 v143, 0x50, v203
	v_cndmask_b32_e32 v150, 0, v66, vcc
	v_cvt_pk_bf16_f32 v66, v50, v51
	v_cvt_pk_bf16_f32 v195, v60, v61
	v_cvt_pk_bf16_f32 v196, v62, v63
	s_waitcnt lgkmcnt(0)
	v_mfma_f32_32x32x16_bf16 v[66:81], v[70:73], v[66:69], 0
	v_cvt_pk_bf16_f32 v197, v64, v65
	v_xad_u32 v143, v143, v201, v205
	v_or_b32_e32 v167, 25, v86
	v_cmp_le_u32_e32 vcc, v167, v84
	v_or_b32_e32 v163, 26, v86
	v_or_b32_e32 v87, 27, v86
	v_cndmask_b32_e32 v142, 0, v151, vcc
	v_mfma_f32_32x32x16_bf16 v[66:81], v[146:149], v[194:197], v[66:81]
	ds_read_b64 v[194:195], v143
	v_cvt_pk_bf16_f32 v146, v34, v35
	v_cvt_pk_bf16_f32 v147, v36, v37
	v_cvt_pk_bf16_f32 v148, v38, v39
	v_cvt_pk_bf16_f32 v149, v40, v41
	v_perm_b32 v142, v142, v150, s45
	v_or_b32_e32 v143, 0x60, v203
	s_waitcnt lgkmcnt(0)
	v_mfma_f32_32x32x16_bf16 v[66:81], v[192:195], v[146:149], v[66:81]
	v_or_b32_e32 v150, 0x70, v203
	v_or_b32_e32 v151, 0x90, v203
	v_xad_u32 v143, v143, v201, v205
	v_xad_u32 v150, v150, v201, v205
	v_xad_u32 v151, v151, v201, v205
	ds_read_b64 v[196:197], v143
	ds_read_b64 v[198:199], v150
	ds_read_b64 v[150:151], v151
	v_cvt_pk_bf16_f32 v146, v42, v43
	v_cvt_pk_bf16_f32 v147, v44, v45
	v_cvt_pk_bf16_f32 v148, v46, v47
	v_cvt_pk_bf16_f32 v149, v48, v49
	v_or_b32_e32 v143, 0xa0, v203
	v_xad_u32 v143, v143, v201, v205
	s_waitcnt lgkmcnt(0)
	v_mfma_f32_32x32x16_bf16 v[66:81], v[196:199], v[146:149], v[66:81]
	v_mov_b32_e32 v148, v144
	v_mov_b32_e32 v149, v145
	v_cvt_pk_bf16_f32 v144, v18, v19
	v_cvt_pk_bf16_f32 v145, v20, v21
	v_cvt_pk_bf16_f32 v146, v22, v23
	v_cvt_pk_bf16_f32 v147, v24, v25
	v_or_b32_e32 v192, 0xd0, v203
	v_xad_u32 v194, v192, v201, v205
	v_mfma_f32_32x32x16_bf16 v[66:81], v[148:151], v[144:147], v[66:81]
	v_or_b32_e32 v146, 0xb0, v203
	v_xad_u32 v146, v146, v201, v205
	ds_read_b64 v[148:149], v143
	ds_read_b64 v[150:151], v146
	v_cvt_pk_bf16_f32 v144, v26, v27
	v_cvt_pk_bf16_f32 v145, v28, v29
	v_cvt_pk_bf16_f32 v146, v30, v31
	v_cvt_pk_bf16_f32 v147, v32, v33
	v_or_b32_e32 v143, 0xc0, v203
	v_xad_u32 v143, v143, v201, v205
	s_waitcnt lgkmcnt(0)
	v_mfma_f32_32x32x16_bf16 v[66:81], v[148:151], v[144:147], v[66:81]
	ds_read_b64 v[192:193], v143
	ds_read_b64 v[194:195], v194
	v_cvt_pk_bf16_f32 v82, v82, s0
	v_cmp_le_u32_e32 vcc, v163, v84
	v_cvt_pk_bf16_f32 v83, v83, s0
	v_cvt_pk_bf16_f32 v144, v2, v3
	v_cndmask_b32_e32 v82, 0, v82, vcc
	v_cmp_le_u32_e32 vcc, v87, v84
	v_cvt_pk_bf16_f32 v145, v4, v5
	v_cvt_pk_bf16_f32 v146, v6, v7
	v_cvt_pk_bf16_f32 v147, v8, v9
	v_cndmask_b32_e32 v83, 0, v83, vcc
	v_perm_b32 v143, v83, v82, s45
	s_waitcnt lgkmcnt(0)
	v_mfma_f32_32x32x16_bf16 v[66:81], v[192:195], v[144:147], v[66:81]
	v_or_b32_e32 v82, 0xe0, v203
	v_xad_u32 v82, v82, v201, v205
	v_or_b32_e32 v83, 0xf0, v203
	v_xad_u32 v83, v83, v201, v205
	ds_read_b64 v[144:145], v82
	ds_read_b64 v[146:147], v83
	v_cvt_pk_bf16_f32 v148, v10, v11
	v_cvt_pk_bf16_f32 v149, v12, v13
	v_cvt_pk_bf16_f32 v150, v14, v15
	v_cvt_pk_bf16_f32 v151, v16, v17
	v_add_u32_e32 v202, s7, v204
	s_add_i32 s14, s20, -2
	s_waitcnt lgkmcnt(0)
	v_mfma_f32_32x32x16_bf16 v[66:81], v[144:147], v[148:151], v[66:81]
	ds_read_b64_tr_b16 v[144:145], v202 offset:0
	ds_read_b64_tr_b16 v[146:147], v202 offset:0x800
	ds_read_b64_tr_b16 v[148:149], v202 offset:0x1000
	ds_read_b64_tr_b16 v[150:151], v202 offset:0x1800
	s_waitcnt lgkmcnt(0)
	v_permlane32_swap_b32_e32 v152, v154
	v_permlane32_swap_b32_e32 v153, v155
	v_permlane32_swap_b32_e32 v140, v142
	v_permlane32_swap_b32_e32 v141, v143
	v_add_u32_e32 v82, 0, v200
	v_add_u32_e32 v83, 0x14400, v82
	v_mfma_f32_32x32x16_bf16 v[66:81], v[152:155], v[144:147], v[66:81]
	ds_read_b128 v[152:155], v83
	v_add_u32_e32 v83, 0x14420, v82
	ds_read_b128 v[192:195], v83
	v_add_u32_e32 v83, 0x14440, v82
	ds_read_b128 v[196:199], v83
	v_add_u32_e32 v83, 0x14460, v82
	ds_read_b128 v[200:203], v83
	s_waitcnt lgkmcnt(0)
	v_pk_mul_f32 v[50:51], v[50:51], v[152:153]
	v_add_u32_e32 v83, s51, v204
	ds_read_b64_tr_b16 v[152:153], v83 offset:0
	v_pk_mul_f32 v[52:53], v[52:53], v[154:155]
	ds_read_b64_tr_b16 v[154:155], v83 offset:0x800
	v_pk_mul_f32 v[54:55], v[54:55], v[192:193]
	ds_read_b64_tr_b16 v[192:193], v83 offset:0x1000
	v_pk_mul_f32 v[56:57], v[56:57], v[194:195]
	ds_read_b64_tr_b16 v[194:195], v83 offset:0x1800
	s_waitcnt lgkmcnt(0)
	v_pk_mul_f32 v[62:63], v[62:63], v[200:201]
	v_pk_mul_f32 v[58:59], v[58:59], v[196:197]
	v_pk_mul_f32 v[64:65], v[64:65], v[202:203]
	v_pk_mul_f32 v[60:61], v[60:61], v[198:199]
	s_nop 1
	v_mfma_f32_32x32x16_bf16 v[50:65], v[152:155], v[144:147], v[50:65]
	v_add_u32_e32 v152, 0x14480, v82
	ds_read_b128 v[152:155], v152
	v_add_u32_e32 v196, 0x144c0, v82
	v_add_u32_e32 v200, 0x144e0, v82
	ds_read_b128 v[196:199], v196
	ds_read_b128 v[200:203], v200
	s_waitcnt lgkmcnt(0)
	v_pk_mul_f32 v[42:43], v[42:43], v[196:197]
	v_mfma_f32_32x32x16_bf16 v[50:65], v[192:195], v[148:151], v[50:65]
	v_add_u32_e32 v192, 0x144a0, v82
	ds_read_b128 v[192:195], v192
	v_mul_f32_e64 v34, v34, v152
	v_mul_f32_e64 v35, v35, v153
	ds_read_b64_tr_b16 v[152:153], v83 offset:0x200
	v_mul_f32_e64 v36, v36, v154
	v_mul_f32_e64 v37, v37, v155
	ds_read_b64_tr_b16 v[154:155], v83 offset:0xa00
	s_waitcnt lgkmcnt(0)
	v_pk_mul_f32 v[38:39], v[38:39], v[192:193]
	ds_read_b64_tr_b16 v[192:193], v83 offset:0x1200
	v_pk_mul_f32 v[40:41], v[40:41], v[194:195]
	ds_read_b64_tr_b16 v[194:195], v83 offset:0x1a00
	s_waitcnt lgkmcnt(0)
	v_pk_mul_f32 v[46:47], v[46:47], v[200:201]
	v_pk_mul_f32 v[48:49], v[48:49], v[202:203]
	v_pk_mul_f32 v[44:45], v[44:45], v[198:199]
	s_nop 1
	v_mfma_f32_32x32x16_bf16 v[34:49], v[152:155], v[144:147], v[34:49]
	v_add_u32_e32 v152, 0x14500, v82
	ds_read_b128 v[152:155], v152
	v_add_u32_e32 v196, 0x14540, v82
	v_add_u32_e32 v200, 0x14560, v82
	ds_read_b128 v[196:199], v196
	ds_read_b128 v[200:203], v200
	s_waitcnt lgkmcnt(0)
	v_pk_mul_f32 v[26:27], v[26:27], v[196:197]
	v_mfma_f32_32x32x16_bf16 v[34:49], v[192:195], v[148:151], v[34:49]
	v_add_u32_e32 v192, 0x14520, v82
	ds_read_b128 v[192:195], v192
	v_mul_f32_e64 v18, v18, v152
	v_mul_f32_e64 v19, v19, v153
	ds_read_b64_tr_b16 v[152:153], v83 offset:0x400
	v_mul_f32_e64 v20, v20, v154
	v_mul_f32_e64 v21, v21, v155
	ds_read_b64_tr_b16 v[154:155], v83 offset:0xc00
	s_waitcnt lgkmcnt(0)
	v_pk_mul_f32 v[22:23], v[22:23], v[192:193]
	ds_read_b64_tr_b16 v[192:193], v83 offset:0x1400
	v_pk_mul_f32 v[24:25], v[24:25], v[194:195]
	ds_read_b64_tr_b16 v[194:195], v83 offset:0x1c00
	s_waitcnt lgkmcnt(0)
	v_pk_mul_f32 v[30:31], v[30:31], v[200:201]
	v_pk_mul_f32 v[32:33], v[32:33], v[202:203]
	v_pk_mul_f32 v[28:29], v[28:29], v[198:199]
	s_nop 1
	v_mfma_f32_32x32x16_bf16 v[18:33], v[152:155], v[144:147], v[18:33]
	v_add_u32_e32 v152, 0x14580, v82
	ds_read_b128 v[152:155], v152
	v_add_u32_e32 v196, 0x145c0, v82
	ds_read_b128 v[196:199], v196
	s_waitcnt lgkmcnt(0)
	v_pk_mul_f32 v[10:11], v[10:11], v[196:197]
	v_mfma_f32_32x32x16_bf16 v[18:33], v[192:195], v[148:151], v[18:33]
	v_add_u32_e32 v192, 0x145a0, v82
	v_add_u32_e32 v82, 0x145e0, v82
	ds_read_b128 v[192:195], v192
	ds_read_b128 v[200:203], v82
	v_mul_f32_e64 v2, v2, v152
	v_mul_f32_e64 v3, v3, v153
	v_pk_mul_f32 v[4:5], v[4:5], v[154:155]
	v_pk_mul_f32 v[12:13], v[12:13], v[198:199]
	v_mfma_f32_32x32x16_bf16 v[66:81], v[140:143], v[148:151], v[66:81]
	ds_read_b64_tr_b16 v[140:141], v83 offset:0x600
	ds_read_b64_tr_b16 v[142:143], v83 offset:0xe00
	ds_read_b64_tr_b16 v[152:153], v83 offset:0x1600
	ds_read_b64_tr_b16 v[154:155], v83 offset:0x1e00
	s_waitcnt lgkmcnt(0)
	s_waitcnt lgkmcnt(0)
	v_mul_f32_e64 v14, v14, v200
	v_mul_f32_e64 v15, v15, v201
	v_mul_f32_e64 v6, v6, v192
	v_mul_f32_e64 v7, v7, v193
	v_pk_mul_f32 v[16:17], v[16:17], v[202:203]
	v_pk_mul_f32 v[8:9], v[8:9], v[194:195]
	s_add_i32 s15, s48, -1
	s_and_b64 s[0:1], s[12:13], exec
	s_cselect_b32 s0, s14, s15
	v_lshlrev_b32_e32 v84, 1, v84
	s_lshl_b32 s0, s0, 5
	v_lshl_add_u64 v[82:83], s[28:29], 0, v[84:85]
	v_xor_b32_e32 v84, 31, v86
	s_add_i32 s0, s0, s47
	v_cndmask_b32_e64 v84, v84, v86, s[12:13]
	v_or_b32_e32 v84, s0, v84
	v_lshlrev_b32_e32 v84, 11, v84
	v_mfma_f32_32x32x16_bf16 v[2:17], v[140:143], v[144:147], v[2:17]
	v_cvt_pk_bf16_f32 v66, v66, s0
	v_lshl_add_u64 v[140:141], v[82:83], 0, v[84:85]
	global_store_short v[140:141], v66, off
	v_cvt_pk_bf16_f32 v140, v67, s0
	v_or_b32_e32 v66, 1, v86
	v_xor_b32_e32 v67, 30, v86
	v_cndmask_b32_e64 v66, v67, v66, s[12:13]
	v_or_b32_e32 v66, s0, v66
	v_lshlrev_b32_e32 v84, 11, v66
	v_lshl_add_u64 v[66:67], v[82:83], 0, v[84:85]
	global_store_short v[66:67], v140, off
	v_xor_b32_e32 v66, 29, v86
	v_cndmask_b32_e64 v66, v66, v191, s[12:13]
	v_or_b32_e32 v66, s0, v66
	v_lshlrev_b32_e32 v84, 11, v66
	v_cvt_pk_bf16_f32 v68, v68, s0
	v_lshl_add_u64 v[66:67], v[82:83], 0, v[84:85]
	global_store_short v[66:67], v68, off
	v_xor_b32_e32 v66, 28, v86
	v_cndmask_b32_e64 v66, v66, v190, s[12:13]
	v_or_b32_e32 v66, s0, v66
	v_lshlrev_b32_e32 v84, 11, v66
	v_cvt_pk_bf16_f32 v68, v69, s0
	v_lshl_add_u64 v[66:67], v[82:83], 0, v[84:85]
	global_store_short v[66:67], v68, off
	v_xor_b32_e32 v66, 23, v86
	v_cndmask_b32_e64 v66, v66, v189, s[12:13]
	v_or_b32_e32 v66, s0, v66
	v_lshlrev_b32_e32 v84, 11, v66
	v_cvt_pk_bf16_f32 v68, v70, s0
	v_lshl_add_u64 v[66:67], v[82:83], 0, v[84:85]
	global_store_short v[66:67], v68, off
	v_xor_b32_e32 v66, 22, v86
	v_cndmask_b32_e64 v66, v66, v188, s[12:13]
	v_or_b32_e32 v66, s0, v66
	v_lshlrev_b32_e32 v84, 11, v66
	v_cvt_pk_bf16_f32 v68, v71, s0
	v_lshl_add_u64 v[66:67], v[82:83], 0, v[84:85]
	global_store_short v[66:67], v68, off
	v_xor_b32_e32 v66, 21, v86
	v_cndmask_b32_e64 v66, v66, v187, s[12:13]
	v_or_b32_e32 v66, s0, v66
	v_lshlrev_b32_e32 v84, 11, v66
	v_cvt_pk_bf16_f32 v68, v72, s0
	v_lshl_add_u64 v[66:67], v[82:83], 0, v[84:85]
	global_store_short v[66:67], v68, off
	v_xor_b32_e32 v66, 20, v86
	v_cndmask_b32_e64 v66, v66, v186, s[12:13]
	v_or_b32_e32 v66, s0, v66
	v_lshlrev_b32_e32 v84, 11, v66
	v_cvt_pk_bf16_f32 v68, v73, s0
	v_lshl_add_u64 v[66:67], v[82:83], 0, v[84:85]
	global_store_short v[66:67], v68, off
	v_xor_b32_e32 v66, 15, v86
	v_cndmask_b32_e64 v66, v66, v185, s[12:13]
	v_or_b32_e32 v66, s0, v66
	v_lshlrev_b32_e32 v84, 11, v66
	v_cvt_pk_bf16_f32 v68, v74, s0
	v_lshl_add_u64 v[66:67], v[82:83], 0, v[84:85]
	global_store_short v[66:67], v68, off
	v_xor_b32_e32 v66, 14, v86
	v_cndmask_b32_e64 v66, v66, v184, s[12:13]
	v_or_b32_e32 v66, s0, v66
	v_lshlrev_b32_e32 v84, 11, v66
	v_cvt_pk_bf16_f32 v68, v75, s0
	v_lshl_add_u64 v[66:67], v[82:83], 0, v[84:85]
	global_store_short v[66:67], v68, off
	v_xor_b32_e32 v66, 13, v86
	v_cndmask_b32_e64 v66, v66, v183, s[12:13]
	v_or_b32_e32 v66, s0, v66
	v_lshlrev_b32_e32 v84, 11, v66
	v_cvt_pk_bf16_f32 v68, v76, s0
	v_lshl_add_u64 v[66:67], v[82:83], 0, v[84:85]
	global_store_short v[66:67], v68, off
	v_xor_b32_e32 v66, 12, v86
	v_cndmask_b32_e64 v66, v66, v182, s[12:13]
	v_or_b32_e32 v66, s0, v66
	v_lshlrev_b32_e32 v84, 11, v66
	v_cvt_pk_bf16_f32 v68, v77, s0
	v_lshl_add_u64 v[66:67], v[82:83], 0, v[84:85]
	global_store_short v[66:67], v68, off
	v_xor_b32_e32 v66, 7, v86
	v_cndmask_b32_e64 v66, v66, v181, s[12:13]
	v_or_b32_e32 v66, s0, v66
	v_lshlrev_b32_e32 v84, 11, v66
	v_cvt_pk_bf16_f32 v68, v78, s0
	v_lshl_add_u64 v[66:67], v[82:83], 0, v[84:85]
	global_store_short v[66:67], v68, off
	v_xor_b32_e32 v66, 6, v86
	v_cndmask_b32_e64 v66, v66, v167, s[12:13]
	v_or_b32_e32 v66, s0, v66
	v_lshlrev_b32_e32 v84, 11, v66
	v_cvt_pk_bf16_f32 v68, v79, s0
	v_lshl_add_u64 v[66:67], v[82:83], 0, v[84:85]
	global_store_short v[66:67], v68, off
	v_xor_b32_e32 v66, 5, v86
	v_cndmask_b32_e64 v66, v66, v163, s[12:13]
	v_mfma_f32_32x32x16_bf16 v[2:17], v[152:155], v[148:151], v[2:17]
	v_or_b32_e32 v66, s0, v66
	v_lshlrev_b32_e32 v84, 11, v66
	v_cvt_pk_bf16_f32 v68, v80, s0
	v_lshl_add_u64 v[66:67], v[82:83], 0, v[84:85]
	global_store_short v[66:67], v68, off
	v_xor_b32_e32 v66, 4, v86
	v_cndmask_b32_e64 v66, v66, v87, s[12:13]
	v_or_b32_e32 v66, s0, v66
	v_lshlrev_b32_e32 v84, 11, v66
	s_add_i32 s20, s20, 2
	s_add_i32 s48, s48, -2
	v_cvt_pk_bf16_f32 v68, v81, s0
	v_lshl_add_u64 v[66:67], v[82:83], 0, v[84:85]
	s_cmp_gt_u32 s49, 61
	global_store_short v[66:67], v68, off
	s_cbranch_scc1 .LBB0_960
.LBB0_970:
	v_mov_b32_e32 v82, v159
	s_and_b64 vcc, exec, s[8:9]
	s_cbranch_vccnz .LBB0_974
	s_waitcnt vmcnt(32) lgkmcnt(0)
	v_cvt_pk_bf16_f32 v66, v104, v105
	v_cvt_pk_bf16_f32 v67, v106, v107
	v_cvt_pk_bf16_f32 v68, v108, v109
	v_cvt_pk_bf16_f32 v69, v110, v111
	v_and_b32_e32 v87, 63, v82
	v_and_b32_e32 v83, 31, v82
	v_mfma_f32_32x32x16_bf16 v[66:81], v[66:69], v[128:131], 0
	s_nop 11
	v_add_f32_e32 v66, v180, v66
	v_mul_f32_e64 v84, |v66|, s40
	v_exp_f32_e32 v84, v84
	v_add_f32_e32 v67, v180, v67
	v_mul_f32_e64 v86, |v67|, s40
	v_exp_f32_e32 v86, v86
	v_add_f32_e32 v84, 1.0, v84
	v_cmp_gt_f32_e32 vcc, s41, v84
	v_min_f32_e32 v66, 0, v66
	v_add_f32_e32 v86, 1.0, v86
	v_cndmask_b32_e64 v140, 0, 32, vcc
	v_ldexp_f32 v84, v84, v140
	v_log_f32_e32 v84, v84
	v_cmp_gt_f32_e64 s[14:15], s41, v86
	v_cndmask_b32_e32 v140, 0, v179, vcc
	v_add_f32_e32 v68, v180, v68
	v_cndmask_b32_e64 v141, 0, 32, s[14:15]
	v_ldexp_f32 v86, v86, v141
	v_mul_f32_e32 v141, 0x3f317217, v84
	v_fma_f32 v141, v84, s42, -v141
	v_fmac_f32_e32 v141, 0x3377d1cf, v84
	v_log_f32_e32 v86, v86
	v_fmac_f32_e32 v141, 0x3f317217, v84
	v_cmp_lt_f32_e64 vcc, |v84|, s43
	s_nop 1
	v_cndmask_b32_e32 v84, v84, v141, vcc
	v_sub_f32_e32 v84, v84, v140
	v_sub_f32_e32 v66, v66, v84
	v_fma_f32 v84, v66, s44, 0
	v_min_f32_e32 v66, 0, v67
	v_mul_f32_e32 v67, 0x3f317217, v86
	v_mul_f32_e64 v140, |v68|, s40
	v_fma_f32 v67, v86, s42, -v67
	v_exp_f32_e32 v140, v140
	v_fmac_f32_e32 v67, 0x3377d1cf, v86
	v_fmac_f32_e32 v67, 0x3f317217, v86
	v_cmp_lt_f32_e64 vcc, |v86|, s43
	s_nop 1
	v_cndmask_b32_e32 v67, v86, v67, vcc
	v_cndmask_b32_e64 v86, 0, v179, s[14:15]
	v_sub_f32_e32 v67, v67, v86
	v_add_f32_e32 v86, 1.0, v140
	v_cmp_gt_f32_e32 vcc, s41, v86
	v_sub_f32_e32 v66, v66, v67
	s_nop 0
	v_cndmask_b32_e64 v140, 0, 32, vcc
	v_ldexp_f32 v86, v86, v140
	v_log_f32_e32 v86, v86
	v_fmamk_f32 v140, v66, 0x3d800000, v84
	v_min_f32_e32 v66, 0, v68
	v_add_f32_e32 v68, v180, v69
	v_mul_f32_e64 v69, |v68|, s40
	v_exp_f32_e32 v69, v69
	v_mul_f32_e32 v67, 0x3f317217, v86
	v_fma_f32 v67, v86, s42, -v67
	v_fmac_f32_e32 v67, 0x3377d1cf, v86
	v_fmac_f32_e32 v67, 0x3f317217, v86
	v_cmp_lt_f32_e64 s[14:15], |v86|, s43
	v_add_f32_e32 v69, 1.0, v69
	s_nop 0
	v_cndmask_b32_e64 v67, v86, v67, s[14:15]
	v_cndmask_b32_e32 v86, 0, v179, vcc
	v_cmp_gt_f32_e32 vcc, s41, v69
	v_sub_f32_e32 v67, v67, v86
	v_sub_f32_e32 v66, v66, v67
	v_cndmask_b32_e64 v86, 0, 32, vcc
	v_ldexp_f32 v69, v69, v86
	v_log_f32_e32 v69, v69
	v_fmamk_f32 v86, v66, 0x3d800000, v140
	v_min_f32_e32 v66, 0, v68
	v_add_f32_e32 v68, v180, v70
	v_mul_f32_e32 v67, 0x3f317217, v69
	v_mul_f32_e64 v70, |v68|, s40
	v_fma_f32 v67, v69, s42, -v67
	v_exp_f32_e32 v70, v70
	v_fmac_f32_e32 v67, 0x3377d1cf, v69
	v_fmac_f32_e32 v67, 0x3f317217, v69
	v_cmp_lt_f32_e64 s[14:15], |v69|, s43
	s_nop 1
	v_cndmask_b32_e64 v67, v69, v67, s[14:15]
	v_cndmask_b32_e32 v69, 0, v179, vcc
	v_sub_f32_e32 v67, v67, v69
	v_add_f32_e32 v69, 1.0, v70
	v_cmp_gt_f32_e32 vcc, s41, v69
	v_sub_f32_e32 v66, v66, v67
	v_min_f32_e32 v67, 0, v68
	v_cndmask_b32_e64 v70, 0, 32, vcc
	v_ldexp_f32 v69, v69, v70
	v_log_f32_e32 v69, v69
	v_add_f32_e32 v70, v180, v71
	v_mul_f32_e64 v71, |v70|, s40
	v_exp_f32_e32 v71, v71
	v_mul_f32_e32 v68, 0x3f317217, v69
	v_fma_f32 v68, v69, s42, -v68
	v_fmac_f32_e32 v68, 0x3377d1cf, v69
	v_fmac_f32_e32 v68, 0x3f317217, v69
	v_cmp_lt_f32_e64 s[14:15], |v69|, s43
	v_fmamk_f32 v66, v66, 0x3d800000, v86
	s_nop 0
	v_cndmask_b32_e64 v68, v69, v68, s[14:15]
	v_cndmask_b32_e32 v69, 0, v179, vcc
	v_sub_f32_e32 v68, v68, v69
	v_add_f32_e32 v69, 1.0, v71
	v_cmp_gt_f32_e32 vcc, s41, v69
	v_sub_f32_e32 v67, v67, v68
	v_fma_f32 v141, v67, s44, 0
	v_cndmask_b32_e64 v71, 0, 32, vcc
	v_ldexp_f32 v69, v69, v71
	v_log_f32_e32 v69, v69
	v_min_f32_e32 v67, 0, v70
	v_add_f32_e32 v70, v180, v72
	v_mul_f32_e64 v71, |v70|, s40
	v_mul_f32_e32 v68, 0x3f317217, v69
	v_fma_f32 v68, v69, s42, -v68
	v_exp_f32_e32 v71, v71
	v_fmac_f32_e32 v68, 0x3377d1cf, v69
	v_fmac_f32_e32 v68, 0x3f317217, v69
	v_cmp_lt_f32_e64 s[14:15], |v69|, s43
	s_nop 1
	v_cndmask_b32_e64 v68, v69, v68, s[14:15]
	v_cndmask_b32_e32 v69, 0, v179, vcc
	v_sub_f32_e32 v68, v68, v69
	v_add_f32_e32 v69, 1.0, v71
	v_cmp_gt_f32_e32 vcc, s41, v69
	v_sub_f32_e32 v67, v67, v68
	v_fmamk_f32 v142, v67, 0x3d800000, v141
	v_cndmask_b32_e64 v71, 0, 32, vcc
	v_ldexp_f32 v69, v69, v71
	v_log_f32_e32 v69, v69
	v_min_f32_e32 v67, 0, v70
	v_add_f32_e32 v70, v180, v73
	v_mul_f32_e64 v71, |v70|, s40
	v_mul_f32_e32 v68, 0x3f317217, v69
	v_fma_f32 v68, v69, s42, -v68
	v_exp_f32_e32 v71, v71
	v_fmac_f32_e32 v68, 0x3377d1cf, v69
	v_fmac_f32_e32 v68, 0x3f317217, v69
	v_cmp_lt_f32_e64 s[14:15], |v69|, s43
	s_nop 1
	v_cndmask_b32_e64 v68, v69, v68, s[14:15]
	v_cndmask_b32_e32 v69, 0, v179, vcc
	v_sub_f32_e32 v68, v68, v69
	v_add_f32_e32 v69, 1.0, v71
	v_cmp_gt_f32_e32 vcc, s41, v69
	v_sub_f32_e32 v67, v67, v68
	v_fmamk_f32 v143, v67, 0x3d800000, v142
	v_cndmask_b32_e64 v71, 0, 32, vcc
	v_ldexp_f32 v69, v69, v71
	v_log_f32_e32 v69, v69
	v_min_f32_e32 v67, 0, v70
	v_add_f32_e32 v70, v180, v74
	v_mul_f32_e64 v71, |v70|, s40
	v_mul_f32_e32 v68, 0x3f317217, v69
	v_fma_f32 v68, v69, s42, -v68
	v_exp_f32_e32 v71, v71
	v_fmac_f32_e32 v68, 0x3377d1cf, v69
	v_fmac_f32_e32 v68, 0x3f317217, v69
	v_cmp_lt_f32_e64 s[14:15], |v69|, s43
	s_nop 1
	v_cndmask_b32_e64 v68, v69, v68, s[14:15]
	v_cndmask_b32_e32 v69, 0, v179, vcc
	v_sub_f32_e32 v68, v68, v69
	v_add_f32_e32 v69, 1.0, v71
	v_cmp_gt_f32_e32 vcc, s41, v69
	v_sub_f32_e32 v67, v67, v68
	v_min_f32_e32 v68, 0, v70
	v_cndmask_b32_e64 v71, 0, 32, vcc
	v_ldexp_f32 v69, v69, v71
	v_log_f32_e32 v69, v69
	v_add_f32_e32 v71, v180, v75
	v_mul_f32_e64 v72, |v71|, s40
	v_exp_f32_e32 v72, v72
	v_mul_f32_e32 v70, 0x3f317217, v69
	v_fma_f32 v70, v69, s42, -v70
	v_fmac_f32_e32 v70, 0x3377d1cf, v69
	v_fmac_f32_e32 v70, 0x3f317217, v69
	v_cmp_lt_f32_e64 s[14:15], |v69|, s43
	v_fmamk_f32 v67, v67, 0x3d800000, v143
	s_nop 0
	v_cndmask_b32_e64 v69, v69, v70, s[14:15]
	v_cndmask_b32_e32 v70, 0, v179, vcc
	v_sub_f32_e32 v69, v69, v70
	v_add_f32_e32 v70, 1.0, v72
	v_cmp_gt_f32_e32 vcc, s41, v70
	v_sub_f32_e32 v68, v68, v69
	v_fma_f32 v75, v68, s44, 0
	v_cndmask_b32_e64 v72, 0, 32, vcc
	v_ldexp_f32 v70, v70, v72
	v_log_f32_e32 v70, v70
	v_min_f32_e32 v68, 0, v71
	v_add_f32_e32 v71, v180, v76
	v_mul_f32_e64 v72, |v71|, s40
	v_mul_f32_e32 v69, 0x3f317217, v70
	v_fma_f32 v69, v70, s42, -v69
	v_exp_f32_e32 v72, v72
	v_fmac_f32_e32 v69, 0x3377d1cf, v70
	v_fmac_f32_e32 v69, 0x3f317217, v70
	v_cmp_lt_f32_e64 s[14:15], |v70|, s43
	s_nop 1
	v_cndmask_b32_e64 v69, v70, v69, s[14:15]
	v_cndmask_b32_e32 v70, 0, v179, vcc
	v_sub_f32_e32 v69, v69, v70
	v_add_f32_e32 v70, 1.0, v72
	v_cmp_gt_f32_e32 vcc, s41, v70
	v_sub_f32_e32 v68, v68, v69
	v_fmamk_f32 v76, v68, 0x3d800000, v75
	v_cndmask_b32_e64 v72, 0, 32, vcc
	v_ldexp_f32 v70, v70, v72
	v_log_f32_e32 v70, v70
	v_min_f32_e32 v68, 0, v71
	v_add_f32_e32 v71, v180, v77
	v_mul_f32_e64 v72, |v71|, s40
	v_mul_f32_e32 v69, 0x3f317217, v70
	v_fma_f32 v69, v70, s42, -v69
	v_exp_f32_e32 v72, v72
	v_fmac_f32_e32 v69, 0x3377d1cf, v70
	v_fmac_f32_e32 v69, 0x3f317217, v70
	v_cmp_lt_f32_e64 s[14:15], |v70|, s43
	s_nop 1
	v_cndmask_b32_e64 v69, v70, v69, s[14:15]
	v_cndmask_b32_e32 v70, 0, v179, vcc
	v_sub_f32_e32 v69, v69, v70
	v_add_f32_e32 v70, 1.0, v72
	v_cmp_gt_f32_e32 vcc, s41, v70
	v_sub_f32_e32 v68, v68, v69
	v_fmamk_f32 v77, v68, 0x3d800000, v76
	v_cndmask_b32_e64 v72, 0, 32, vcc
	v_ldexp_f32 v70, v70, v72
	v_log_f32_e32 v70, v70
	v_min_f32_e32 v68, 0, v71
	v_add_f32_e32 v71, v180, v78
	v_mul_f32_e64 v72, |v71|, s40
	v_mul_f32_e32 v69, 0x3f317217, v70
	v_fma_f32 v69, v70, s42, -v69
	v_exp_f32_e32 v72, v72
	v_fmac_f32_e32 v69, 0x3377d1cf, v70
	v_fmac_f32_e32 v69, 0x3f317217, v70
	v_cmp_lt_f32_e64 s[14:15], |v70|, s43
	s_nop 1
	v_cndmask_b32_e64 v69, v70, v69, s[14:15]
	v_cndmask_b32_e32 v70, 0, v179, vcc
	v_sub_f32_e32 v69, v69, v70
	v_add_f32_e32 v70, 1.0, v72
	v_cmp_gt_f32_e32 vcc, s41, v70
	v_sub_f32_e32 v68, v68, v69
	v_min_f32_e32 v69, 0, v71
	v_cndmask_b32_e64 v72, 0, 32, vcc
	v_ldexp_f32 v70, v70, v72
	v_log_f32_e32 v70, v70
	v_add_f32_e32 v72, v180, v79
	v_mul_f32_e64 v73, |v72|, s40
	v_exp_f32_e32 v73, v73
	v_mul_f32_e32 v71, 0x3f317217, v70
	v_fma_f32 v71, v70, s42, -v71
	v_fmac_f32_e32 v71, 0x3377d1cf, v70
	v_fmac_f32_e32 v71, 0x3f317217, v70
	v_cmp_lt_f32_e64 s[14:15], |v70|, s43
	v_fmamk_f32 v68, v68, 0x3d800000, v77
	s_nop 0
	v_cndmask_b32_e64 v70, v70, v71, s[14:15]
	v_cndmask_b32_e32 v71, 0, v179, vcc
	v_sub_f32_e32 v70, v70, v71
	v_add_f32_e32 v71, 1.0, v73
	v_cmp_gt_f32_e32 vcc, s41, v71
	v_sub_f32_e32 v69, v69, v70
	v_fma_f32 v78, v69, s44, 0
	v_cndmask_b32_e64 v73, 0, 32, vcc
	v_ldexp_f32 v71, v71, v73
	v_log_f32_e32 v71, v71
	v_min_f32_e32 v69, 0, v72
	v_add_f32_e32 v72, v180, v80
	v_mul_f32_e64 v73, |v72|, s40
	v_mul_f32_e32 v70, 0x3f317217, v71
	v_fma_f32 v70, v71, s42, -v70
	v_exp_f32_e32 v73, v73
	v_fmac_f32_e32 v70, 0x3377d1cf, v71
	v_fmac_f32_e32 v70, 0x3f317217, v71
	v_cmp_lt_f32_e64 s[14:15], |v71|, s43
	s_nop 1
	v_cndmask_b32_e64 v70, v71, v70, s[14:15]
	v_cndmask_b32_e32 v71, 0, v179, vcc
	v_sub_f32_e32 v70, v70, v71
	v_add_f32_e32 v71, 1.0, v73
	v_cmp_gt_f32_e32 vcc, s41, v71
	v_sub_f32_e32 v69, v69, v70
	v_fmamk_f32 v79, v69, 0x3d800000, v78
	v_cndmask_b32_e64 v73, 0, 32, vcc
	v_ldexp_f32 v71, v71, v73
	v_log_f32_e32 v71, v71
	v_min_f32_e32 v69, 0, v72
	v_add_f32_e32 v72, v180, v81
	v_mul_f32_e64 v73, |v72|, s40
	v_mul_f32_e32 v70, 0x3f317217, v71
	v_fma_f32 v70, v71, s42, -v70
	v_exp_f32_e32 v73, v73
	v_fmac_f32_e32 v70, 0x3377d1cf, v71
	v_fmac_f32_e32 v70, 0x3f317217, v71
	v_cmp_lt_f32_e64 s[14:15], |v71|, s43
	s_nop 1
	v_cndmask_b32_e64 v70, v71, v70, s[14:15]
	v_cndmask_b32_e32 v71, 0, v179, vcc
	v_sub_f32_e32 v70, v70, v71
	v_add_f32_e32 v71, 1.0, v73
	v_cmp_gt_f32_e32 vcc, s41, v71
	v_sub_f32_e32 v69, v69, v70
	v_fmamk_f32 v80, v69, 0x3d800000, v79
	v_cndmask_b32_e64 v73, 0, 32, vcc
	v_ldexp_f32 v71, v71, v73
	v_log_f32_e32 v71, v71
	v_min_f32_e32 v69, 0, v72
	v_mov_b32_e32 v72, v67
	v_mov_b32_e32 v73, v68
	v_mul_f32_e32 v70, 0x3f317217, v71
	v_fma_f32 v70, v71, s42, -v70
	v_fmac_f32_e32 v70, 0x3377d1cf, v71
	v_fmac_f32_e32 v70, 0x3f317217, v71
	v_cmp_lt_f32_e64 s[14:15], |v71|, s43
	s_nop 1
	v_cndmask_b32_e64 v70, v71, v70, s[14:15]
	v_cndmask_b32_e32 v71, 0, v179, vcc
	v_sub_f32_e32 v70, v70, v71
	v_sub_f32_e32 v69, v69, v70
	v_mov_b32_e32 v70, v66
	v_mov_b32_e32 v71, v66
	s_nop 1
	v_permlane32_swap_b32_e32 v70, v71
	v_cmp_gt_u32_e32 vcc, 32, v87
	v_fmamk_f32 v69, v69, 0x3d800000, v80
	v_mov_b32_e32 v74, v69
	v_cndmask_b32_e32 v70, v70, v71, vcc
	v_mov_b32_e32 v71, v67
	s_nop 1
	v_permlane32_swap_b32_e32 v71, v72
	v_cndmask_b32_e32 v71, v71, v72, vcc
	v_mov_b32_e32 v72, v68
	s_nop 1
	v_permlane32_swap_b32_e32 v72, v73
	v_cndmask_b32_e32 v72, v72, v73, vcc
	v_mov_b32_e32 v73, v69
	s_nop 1
	v_permlane32_swap_b32_e32 v73, v74
	v_cndmask_b32_e32 v74, v73, v74, vcc
	v_lshlrev_b32_e32 v73, 6, v82
	v_cndmask_b32_e64 v81, v70, 0, vcc
	v_and_b32_e32 v82, 0x800, v73
	v_lshlrev_b32_e32 v73, 2, v83
	v_add_f32_e32 v83, v81, v84
	v_add3_u32 v82, s4, v73, v82
	v_add_f32_e32 v84, v81, v140
	ds_write2st64_b32 v82, v83, v84 offset1:2
	v_add_f32_e32 v83, v81, v86
	v_add_f32_e32 v84, v81, v66
	ds_write2st64_b32 v82, v83, v84 offset0:4 offset1:6
	v_cndmask_b32_e32 v83, v71, v70, vcc
	v_add_f32_e32 v83, v83, v66
	v_add_f32_e32 v81, v81, v83
	v_add_f32_e32 v83, v141, v81
	v_add_f32_e32 v84, v142, v81
	ds_write2st64_b32 v82, v83, v84 offset0:16 offset1:18
	v_add_f32_e32 v83, v143, v81
	v_add_f32_e32 v84, v67, v81
	ds_write2st64_b32 v82, v83, v84 offset0:20 offset1:22
	v_cndmask_b32_e32 v83, v72, v71, vcc
	v_add_f32_e32 v83, v83, v67
	v_add_f32_e32 v81, v83, v81
	v_add_f32_e32 v75, v75, v81
	v_add_f32_e32 v76, v76, v81
	ds_write2st64_b32 v82, v75, v76 offset0:32 offset1:34
	v_add_f32_e32 v75, v77, v81
	v_add_f32_e32 v76, v68, v81
	ds_write2st64_b32 v82, v75, v76 offset0:36 offset1:38
	v_cndmask_b32_e32 v75, v74, v72, vcc
	v_add_f32_e32 v75, v75, v68
	v_add_f32_e32 v75, v75, v81
	v_add_f32_e32 v76, v78, v75
	v_add_f32_e32 v77, v79, v75
	ds_write2st64_b32 v82, v76, v77 offset0:48 offset1:50
	v_add_f32_e32 v76, v80, v75
	v_add_f32_e32 v75, v69, v75
	ds_write2st64_b32 v82, v76, v75 offset0:52 offset1:54
	s_and_saveexec_b64 s[14:15], vcc
	s_cbranch_execz .LBB0_973
	v_add_f32_e32 v66, v66, v67
	v_add_f32_e32 v67, v68, v69
	v_add_f32_e32 v66, v66, v67
	v_add_f32_e32 v67, v70, v71
	v_add_f32_e32 v66, v67, v66
	v_add_f32_e32 v67, v72, v74
	v_add_f32_e32 v66, v67, v66
	v_mul_f32_e32 v67, 0x3fb8aa3b, v66
	v_exp_f32_e32 v67, v67
	v_add_u32_e32 v68, s5, v73
	ds_write_b32 v68, v66
	v_add_u32_e32 v66, s6, v73
	ds_write_b32 v66, v67

.LBB0_974:
	v_mov_b32_e32 v66, v159
	s_waitcnt lgkmcnt(0)
	s_barrier
	s_add_i32 s50, 0, 0x10000
	v_ashrrev_i32_e32 v67, 5, v66
	v_lshlrev_b32_e32 v68, 10, v66
	v_and_b32_e32 v70, 0xfffff0, v67
	v_lshlrev_b32_e32 v71, 1, v67
	v_and_b32_e32 v69, 0x4000, v68
	v_lshlrev_b32_e32 v68, 3, v66
	v_and_or_b32 v70, v71, 8, v70
	v_lshrrev_b32_e32 v71, 1, v67
	v_and_b32_e32 v73, 3, v67
	v_lshrrev_b32_e32 v70, 1, v70
	v_bfe_u32 v72, v68, 5, 2
	v_and_or_b32 v71, v71, 4, v73
	v_or_b32_e32 v70, v70, v72
	v_lshlrev_b32_e32 v71, 6, v71
	v_lshlrev_b32_e32 v73, 4, v66
	v_lshlrev_b32_e32 v70, 9, v70
	v_and_b32_e32 v73, 48, v73
	v_add3_u32 v71, 0, v69, v71
	v_add3_u32 v69, v71, v70, v73
	s_waitcnt vmcnt(32)
	ds_write_b128 v69, v[96:99] offset:32768
	v_add_u32_e32 v69, 16, v67
	v_and_b32_e32 v70, 0xfffff0, v69
	v_lshlrev_b32_e32 v74, 1, v69
	v_and_or_b32 v70, v74, 8, v70
	v_lshrrev_b32_e32 v70, 1, v70
	v_or_b32_e32 v70, v70, v72
	v_lshlrev_b32_e32 v70, 9, v70
	v_add3_u32 v70, v71, v70, v73
	ds_write_b128 v70, v[100:103] offset:32768
	v_ashrrev_i32_e32 v70, 4, v66
	v_and_b32_e32 v71, 15, v66
	v_lshlrev_b32_e32 v72, 9, v70
	v_lshlrev_b32_e32 v73, 5, v71
	v_add3_u32 v76, s50, v72, v73
	v_add_u32_e32 v72, 0, v73
	v_add_u32_e32 v84, 0x14000, v72
	ds_read_b128 v[72:75], v76
	ds_read_b128 v[76:79], v76 offset:16
	ds_read_b128 v[80:83], v84
	ds_read_b128 v[140:143], v84 offset:16
	v_lshlrev_b32_e32 v84, 16, v88
	s_waitcnt lgkmcnt(3)
	v_mul_f32_e32 v72, 0x3fb8aa3b, v72
	v_exp_f32_e32 v72, v72
	v_mul_f32_e32 v73, 0x3fb8aa3b, v73
	v_mul_f32_e32 v74, 0x3fb8aa3b, v74
	v_mul_f32_e32 v75, 0x3fb8aa3b, v75
	s_waitcnt lgkmcnt(2)
	v_mul_f32_e32 v76, 0x3fb8aa3b, v76
	v_mul_f32_e32 v77, 0x3fb8aa3b, v77
	v_exp_f32_e32 v73, v73
	v_exp_f32_e32 v74, v74
	v_exp_f32_e32 v75, v75
	v_exp_f32_e32 v76, v76
	v_exp_f32_e32 v77, v77
	v_mul_f32_e32 v78, 0x3fb8aa3b, v78
	v_mul_f32_e32 v79, 0x3fb8aa3b, v79
	v_exp_f32_e32 v78, v78
	v_exp_f32_e32 v79, v79
	v_and_b32_e32 v144, 0xffff0000, v88
	v_lshlrev_b32_e32 v145, 16, v89
	v_and_b32_e32 v146, 0xffff0000, v89
	v_lshlrev_b32_e32 v147, 16, v90
	v_and_b32_e32 v148, 0xffff0000, v90
	v_rcp_f32_e32 v86, v72
	v_mul_f32_e32 v72, v72, v84
	s_waitcnt lgkmcnt(0)
	v_mul_f32_e32 v84, 0x3fb8aa3b, v140
	v_rcp_f32_e32 v87, v73
	v_mul_f32_e32 v73, v73, v144
	v_rcp_f32_e32 v144, v74
	v_mul_f32_e32 v74, v74, v145
	v_rcp_f32_e32 v145, v75
	v_mul_f32_e32 v75, v75, v146
	v_rcp_f32_e32 v146, v76
	v_mul_f32_e32 v76, v76, v147
	v_exp_f32_e32 v140, v84
	v_rcp_f32_e32 v147, v77
	v_mul_f32_e32 v77, v77, v148
	v_mul_f32_e32 v84, 0x3fb8aa3b, v141
	v_lshlrev_b32_e32 v149, 16, v91
	v_and_b32_e32 v150, 0xffff0000, v91
	v_mul_f32_e32 v80, 0x3fb8aa3b, v80
	v_mul_f32_e32 v81, 0x3fb8aa3b, v81
	v_exp_f32_e32 v141, v84
	v_mul_f32_e32 v84, 0x3fb8aa3b, v142
	v_cvt_pk_bf16_f32 v72, v72, v73
	v_cvt_pk_bf16_f32 v73, v74, v75
	v_cvt_pk_bf16_f32 v74, v76, v77
	v_lshlrev_b32_e32 v76, 8, v70
	v_lshlrev_b32_e32 v71, 4, v71
	v_and_b32_e32 v77, 0x70, v66
	v_exp_f32_e32 v80, v80
	v_exp_f32_e32 v81, v81
	v_rcp_f32_e32 v148, v78
	v_mul_f32_e32 v78, v78, v149
	v_exp_f32_e32 v142, v84
	v_rcp_f32_e32 v149, v79
	v_mul_f32_e32 v79, v79, v150
	v_mul_f32_e32 v84, 0x3fb8aa3b, v143
	v_bitop3_b32 v76, v71, v76, v77 bitop3:0xde
	v_exp_f32_e32 v143, v84
	v_cvt_pk_bf16_f32 v75, v78, v79
	v_add_u32_e32 v84, 0, v76
	v_mul_f32_e32 v82, 0x3fb8aa3b, v82
	v_mul_f32_e32 v83, 0x3fb8aa3b, v83
	ds_write_b128 v84, v[72:75]
	v_lshlrev_b32_e32 v72, 16, v92
	v_and_b32_e32 v73, 0xffff0000, v92
	v_exp_f32_e32 v82, v82
	v_exp_f32_e32 v83, v83
	v_pk_mul_f32 v[72:73], v[86:87], v[72:73]
	s_add_i32 s49, s20, -3
	v_pk_mul_f32 v[74:75], v[72:73], v[80:81]
	v_cvt_pk_bf16_f32 v72, v72, v73
	v_cvt_pk_bf16_f32 v76, v74, v75
	v_lshlrev_b32_e32 v74, 16, v93
	v_and_b32_e32 v75, 0xffff0000, v93
	v_pk_mul_f32 v[74:75], v[144:145], v[74:75]
	v_lshlrev_b32_e32 v80, 16, v95
	v_pk_mul_f32 v[78:79], v[74:75], v[82:83]
	v_cvt_pk_bf16_f32 v73, v74, v75
	v_lshlrev_b32_e32 v74, 16, v94
	v_and_b32_e32 v75, 0xffff0000, v94
	v_and_b32_e32 v81, 0xffff0000, v95
	v_pk_mul_f32 v[74:75], v[146:147], v[74:75]
	v_pk_mul_f32 v[80:81], v[148:149], v[80:81]
	v_cvt_pk_bf16_f32 v77, v78, v79
	v_pk_mul_f32 v[78:79], v[74:75], v[140:141]
	v_cvt_pk_bf16_f32 v74, v74, v75
	v_cvt_pk_bf16_f32 v75, v80, v81
	ds_write_b128 v84, v[72:75] offset:8192
	v_and_b32_e32 v72, 0xfffff0, v70
	v_lshlrev_b32_e32 v73, 1, v70
	v_and_or_b32 v72, v73, 8, v72
	v_lshrrev_b32_e32 v72, 1, v72
	v_bfe_u32 v74, v66, 2, 2
	v_lshrrev_b32_e32 v73, 1, v70
	v_or_b32_e32 v72, v72, v74
	v_and_b32_e32 v74, 3, v70
	v_and_or_b32 v73, v73, 4, v74
	v_pk_mul_f32 v[82:83], v[80:81], v[142:143]
	v_lshlrev_b32_e32 v73, 6, v73
	v_and_b32_e32 v71, 48, v71
	v_lshl_add_u32 v72, v72, 9, 0
	s_cmp_lt_u32 s49, 62
	v_cvt_pk_bf16_f32 v78, v78, v79
	v_cvt_pk_bf16_f32 v79, v82, v83
	v_add3_u32 v71, v72, v73, v71
	s_cselect_b64 s[36:37], -1, 0
	s_cmp_gt_u32 s49, 61
	ds_write_b128 v71, v[76:79] offset:16384
	s_cbranch_scc1 .LBB0_977
	s_add_i32 s14, s20, -1
	s_add_i32 s15, s48, -2
	s_and_b64 s[0:1], s[12:13], exec
	s_cselect_b32 s0, s14, s15
	s_lshl_b32 s0, s0, 5
	v_sub_u32_e32 v71, 31, v70
	v_cndmask_b32_e64 v70, v71, v70, s[12:13]
	s_add_i32 s0, s0, s47
	v_and_b32_e32 v72, 0x78, v68
	v_add_u32_e32 v73, s0, v70
	v_mov_b64_e32 v[70:71], s[30:31]
	v_mad_i64_i32 v[70:71], s[14:15], v73, s39, v[70:71]
	v_lshlrev_b32_e32 v84, 1, v72
	v_lshl_add_u64 v[70:71], v[70:71], 0, v[84:85]
	global_load_dwordx4 v[88:91], v[70:71], off
	global_load_dwordx4 v[92:95], v[70:71], off offset:1024
	v_sub_u32_e32 v70, 31, v67
	v_cndmask_b32_e64 v70, v70, v67, s[12:13]
	v_sub_u32_e32 v67, 15, v67
	v_add_u32_e32 v72, s0, v70
	v_mov_b64_e32 v[70:71], s[34:35]
	v_and_b32_e32 v68, 0xf8, v68
	v_cndmask_b32_e64 v67, v67, v69, s[12:13]
	v_mad_i64_i32 v[72:73], s[14:15], v72, s39, v[70:71]
	v_lshlrev_b32_e32 v84, 1, v68
	v_add_u32_e32 v67, s0, v67
	v_lshl_add_u64 v[72:73], v[72:73], 0, v[84:85]
	v_mad_i64_i32 v[68:69], s[14:15], v67, s39, v[70:71]
	v_lshl_add_u64 v[68:69], v[68:69], 0, v[84:85]
	global_load_dwordx4 v[96:99], v[72:73], off offset:2048
	global_load_dwordx4 v[100:103], v[68:69], off offset:2048
	s_and_b64 vcc, exec, s[8:9]
	s_cbranch_vccnz .LBB0_977
	v_and_b32_e32 v67, 31, v66
	v_bitop3_b32 v68, v66, 31, v66 bitop3:0xc
	v_cndmask_b32_e64 v67, v68, v67, s[12:13]
	v_or_b32_e32 v67, s0, v67
	v_lshlrev_b32_e32 v84, 7, v67
	v_lshl_add_u64 v[68:69], s[26:27], 0, v[84:85]
	v_and_b32_e32 v84, 32, v66
	v_lshl_add_u64 v[66:67], v[68:69], 0, v[84:85]
	global_load_dwordx4 v[104:107], v[66:67], off
	global_load_dwordx4 v[108:111], v[66:67], off offset:16
.LBB0_977:
	v_mov_b32_e32 v86, v159
	s_waitcnt lgkmcnt(0)
	s_barrier
	v_cvt_pk_bf16_f32 v194, v58, v59
	v_and_b32_e32 v84, 31, v86
	v_bfe_u32 v192, v86, 5, 1
	v_lshlrev_b32_e32 v87, 4, v86
	v_lshlrev_b32_e32 v200, 4, v192
	v_lshlrev_b32_e32 v193, 8, v84
	v_and_b32_e32 v201, 0x70, v87
	v_bitop3_b32 v66, v201, v193, v200 bitop3:0xde
	v_add_u32_e32 v70, 0, v66
	ds_read_b128 v[66:69], v70 offset:8192
	ds_read_b128 v[70:73], v70
	s_waitcnt lgkmcnt(0)
	v_mfma_f32_32x32x16_bf16 v[68:83], v[66:69], v[70:73], 0
	v_or_b32_e32 v66, 32, v200
	v_bitop3_b32 v66, v66, v193, v201 bitop3:0xde
	v_add_u32_e32 v66, 0, v66
	ds_read_b128 v[140:143], v66 offset:8192
	ds_read_b128 v[144:147], v66
	v_or_b32_e32 v66, 64, v200
	v_bitop3_b32 v66, v66, v193, v201 bitop3:0xde
	v_add_u32_e32 v66, 0, v66
	s_waitcnt lgkmcnt(0)
	v_mfma_f32_32x32x16_bf16 v[68:83], v[140:143], v[144:147], v[68:83]
	ds_read_b128 v[140:143], v66 offset:8192
	ds_read_b128 v[144:147], v66
	v_or_b32_e32 v66, 0x60, v200
	v_bitop3_b32 v66, v66, v193, v201 bitop3:0xde
	v_add_u32_e32 v66, 0, v66
	ds_read_b128 v[148:151], v66 offset:8192
	v_and_b32_e32 v67, 63, v86
	v_lshlrev_b32_e32 v67, 3, v67
	s_waitcnt lgkmcnt(0)
	v_mfma_f32_32x32x16_bf16 v[68:83], v[140:143], v[144:147], v[68:83]
	ds_read_b128 v[140:143], v66
	v_or_b32_e32 v66, 0x80, v200
	v_bitop3_b32 v66, v66, v193, v201 bitop3:0xde
	v_add_u32_e32 v66, 0, v66
	ds_read_b128 v[144:147], v66 offset:8192
	v_and_b32_e32 v87, 0xc0, v87
	v_and_b32_e32 v153, 0x100, v67
	s_waitcnt lgkmcnt(0)
	v_mfma_f32_32x32x16_bf16 v[68:83], v[148:151], v[140:143], v[68:83]
	ds_read_b128 v[140:143], v66
	v_or_b32_e32 v66, 0xa0, v200
	v_bitop3_b32 v66, v66, v193, v201 bitop3:0xde
	v_add_u32_e32 v66, 0, v66
	ds_read_b128 v[148:151], v66 offset:8192
	v_lshlrev_b32_e32 v86, 1, v86
	v_and_b32_e32 v152, 32, v86
	s_waitcnt lgkmcnt(0)
	v_mfma_f32_32x32x16_bf16 v[68:83], v[144:147], v[140:143], v[68:83]
	ds_read_b128 v[140:143], v66
	v_or_b32_e32 v66, 0xc0, v200
	v_bitop3_b32 v66, v66, v193, v201 bitop3:0xde
	v_add_u32_e32 v66, 0, v66
	ds_read_b128 v[144:147], v66 offset:8192
	v_lshlrev_b32_e32 v86, 2, v192
	v_cmp_le_u32_e32 vcc, v86, v84
	s_waitcnt lgkmcnt(0)
	v_mfma_f32_32x32x16_bf16 v[68:83], v[148:151], v[140:143], v[68:83]
	ds_read_b128 v[140:143], v66
	v_or_b32_e32 v148, 0xe0, v200
	v_and_or_b32 v66, v67, 24, v87
	v_bitop3_b32 v67, v148, v193, v201 bitop3:0xde
	v_add_u32_e32 v67, 0, v67
	ds_read_b128 v[148:151], v67 offset:8192
	v_or3_b32 v204, v66, v152, v153
	s_waitcnt lgkmcnt(0)
	v_mfma_f32_32x32x16_bf16 v[68:83], v[144:147], v[140:143], v[68:83]
	ds_read_b128 v[140:143], v67
	v_or_b32_e32 v191, 2, v86
	v_or_b32_e32 v190, 3, v86
	v_or_b32_e32 v189, 8, v86
	v_or_b32_e32 v188, 9, v86
	v_or_b32_e32 v187, 10, v86
	v_lshlrev_b32_e32 v203, 3, v192
	s_waitcnt lgkmcnt(0)
	v_mfma_f32_32x32x16_bf16 v[68:83], v[148:151], v[140:143], v[68:83]
	v_add_u32_e32 v205, 0, v193
	v_or_b32_e32 v186, 11, v86
	v_or_b32_e32 v185, 16, v86
	v_or_b32_e32 v184, 17, v86
	v_or_b32_e32 v183, 18, v86
	v_or_b32_e32 v182, 19, v86
	v_or_b32_e32 v181, 24, v86
	s_nop 4
	v_cvt_pk_bf16_f32 v66, v68, s0
	v_cndmask_b32_e32 v66, 0, v66, vcc
	v_cvt_pk_bf16_f32 v67, v69, s0
	v_cmp_lt_u32_e32 vcc, v86, v84
	v_add3_u32 v69, v205, v201, v203
	ds_read2_b64 v[142:145], v69 offset1:16
	v_cndmask_b32_e32 v67, 0, v67, vcc
	v_perm_b32 v152, v67, v66, s45
	v_cvt_pk_bf16_f32 v66, v70, s0
	v_cmp_le_u32_e32 vcc, v191, v84
	v_cvt_pk_bf16_f32 v67, v71, s0
	v_or_b32_e32 v70, 16, v203
	v_cndmask_b32_e32 v66, 0, v66, vcc
	v_cmp_le_u32_e32 vcc, v190, v84
	v_xad_u32 v70, v70, v201, v205
	s_waitcnt lgkmcnt(0)
	v_mov_b32_e32 v71, v143
	v_cndmask_b32_e32 v67, 0, v67, vcc
	v_perm_b32 v153, v67, v66, s45
	v_cvt_pk_bf16_f32 v66, v72, s0
	v_cmp_le_u32_e32 vcc, v189, v84
	v_cvt_pk_bf16_f32 v67, v73, s0
	ds_read_b64 v[72:73], v70
	v_cndmask_b32_e32 v66, 0, v66, vcc
	v_cmp_le_u32_e32 vcc, v188, v84
	v_mov_b32_e32 v70, v142
	v_cvt_pk_bf16_f32 v68, v54, v55
	v_cndmask_b32_e32 v67, 0, v67, vcc
	v_perm_b32 v154, v67, v66, s45
	v_cvt_pk_bf16_f32 v66, v74, s0
	v_cmp_le_u32_e32 vcc, v187, v84
	v_cvt_pk_bf16_f32 v67, v75, s0
	v_or_b32_e32 v74, 32, v203
	v_cndmask_b32_e32 v66, 0, v66, vcc
	v_cmp_le_u32_e32 vcc, v186, v84
	v_or_b32_e32 v75, 48, v203
	v_cvt_pk_bf16_f32 v69, v56, v57
	v_cndmask_b32_e32 v67, 0, v67, vcc
	v_perm_b32 v155, v67, v66, s45
	v_cvt_pk_bf16_f32 v66, v76, s0
	v_cmp_le_u32_e32 vcc, v185, v84
	v_cvt_pk_bf16_f32 v67, v77, s0
	v_or_b32_e32 v76, 64, v203
	v_cndmask_b32_e32 v66, 0, v66, vcc
	v_cmp_le_u32_e32 vcc, v184, v84
	v_xad_u32 v74, v74, v201, v205
	v_xad_u32 v75, v75, v201, v205
	v_cndmask_b32_e32 v67, 0, v67, vcc
	v_perm_b32 v140, v67, v66, s45
	v_cvt_pk_bf16_f32 v66, v78, s0
	v_cmp_le_u32_e32 vcc, v183, v84
	v_cvt_pk_bf16_f32 v67, v79, s0
	v_xad_u32 v76, v76, v201, v205
	v_cndmask_b32_e32 v66, 0, v66, vcc
	v_cmp_le_u32_e32 vcc, v182, v84
	v_cvt_pk_bf16_f32 v151, v81, s0
	ds_read_b64 v[146:147], v74
	ds_read_b64 v[148:149], v75
	ds_read_b64 v[192:193], v76
	v_cndmask_b32_e32 v67, 0, v67, vcc
	v_perm_b32 v141, v67, v66, s45
	v_cvt_pk_bf16_f32 v66, v80, s0
	v_cmp_le_u32_e32 vcc, v181, v84
	v_cvt_pk_bf16_f32 v67, v52, v53
	v_or_b32_e32 v143, 0x50, v203
	v_cndmask_b32_e32 v150, 0, v66, vcc
	v_cvt_pk_bf16_f32 v66, v50, v51
	v_cvt_pk_bf16_f32 v195, v60, v61
	v_cvt_pk_bf16_f32 v196, v62, v63
	s_waitcnt lgkmcnt(0)
	v_mfma_f32_32x32x16_bf16 v[66:81], v[70:73], v[66:69], 0
	v_cvt_pk_bf16_f32 v197, v64, v65
	v_xad_u32 v143, v143, v201, v205
	v_or_b32_e32 v167, 25, v86
	v_cmp_le_u32_e32 vcc, v167, v84
	v_or_b32_e32 v163, 26, v86
	v_or_b32_e32 v87, 27, v86
	v_cndmask_b32_e32 v142, 0, v151, vcc
	v_mfma_f32_32x32x16_bf16 v[66:81], v[146:149], v[194:197], v[66:81]
	ds_read_b64 v[194:195], v143
	v_cvt_pk_bf16_f32 v146, v34, v35
	v_cvt_pk_bf16_f32 v147, v36, v37
	v_cvt_pk_bf16_f32 v148, v38, v39
	v_cvt_pk_bf16_f32 v149, v40, v41
	v_perm_b32 v142, v142, v150, s45
	v_or_b32_e32 v143, 0x60, v203
	s_waitcnt lgkmcnt(0)
	v_mfma_f32_32x32x16_bf16 v[66:81], v[192:195], v[146:149], v[66:81]
	v_or_b32_e32 v150, 0x70, v203
	v_or_b32_e32 v151, 0x90, v203
	v_xad_u32 v143, v143, v201, v205
	v_xad_u32 v150, v150, v201, v205
	v_xad_u32 v151, v151, v201, v205
	ds_read_b64 v[196:197], v143
	ds_read_b64 v[198:199], v150
	ds_read_b64 v[150:151], v151
	v_cvt_pk_bf16_f32 v146, v42, v43
	v_cvt_pk_bf16_f32 v147, v44, v45
	v_cvt_pk_bf16_f32 v148, v46, v47
	v_cvt_pk_bf16_f32 v149, v48, v49
	v_or_b32_e32 v143, 0xa0, v203
	v_xad_u32 v143, v143, v201, v205
	s_waitcnt lgkmcnt(0)
	v_mfma_f32_32x32x16_bf16 v[66:81], v[196:199], v[146:149], v[66:81]
	v_mov_b32_e32 v148, v144
	v_mov_b32_e32 v149, v145
	v_cvt_pk_bf16_f32 v144, v18, v19
	v_cvt_pk_bf16_f32 v145, v20, v21
	v_cvt_pk_bf16_f32 v146, v22, v23
	v_cvt_pk_bf16_f32 v147, v24, v25
	v_or_b32_e32 v192, 0xd0, v203
	v_xad_u32 v194, v192, v201, v205
	v_mfma_f32_32x32x16_bf16 v[66:81], v[148:151], v[144:147], v[66:81]
	v_or_b32_e32 v146, 0xb0, v203
	v_xad_u32 v146, v146, v201, v205
	ds_read_b64 v[148:149], v143
	ds_read_b64 v[150:151], v146
	v_cvt_pk_bf16_f32 v144, v26, v27
	v_cvt_pk_bf16_f32 v145, v28, v29
	v_cvt_pk_bf16_f32 v146, v30, v31
	v_cvt_pk_bf16_f32 v147, v32, v33
	v_or_b32_e32 v143, 0xc0, v203
	v_xad_u32 v143, v143, v201, v205
	s_waitcnt lgkmcnt(0)
	v_mfma_f32_32x32x16_bf16 v[66:81], v[148:151], v[144:147], v[66:81]
	ds_read_b64 v[192:193], v143
	ds_read_b64 v[194:195], v194
	v_cvt_pk_bf16_f32 v82, v82, s0
	v_cmp_le_u32_e32 vcc, v163, v84
	v_cvt_pk_bf16_f32 v83, v83, s0
	v_cvt_pk_bf16_f32 v144, v2, v3
	v_cndmask_b32_e32 v82, 0, v82, vcc
	v_cmp_le_u32_e32 vcc, v87, v84
	v_cvt_pk_bf16_f32 v145, v4, v5
	v_cvt_pk_bf16_f32 v146, v6, v7
	v_cvt_pk_bf16_f32 v147, v8, v9
	v_cndmask_b32_e32 v83, 0, v83, vcc
	v_perm_b32 v143, v83, v82, s45
	s_waitcnt lgkmcnt(0)
	v_mfma_f32_32x32x16_bf16 v[66:81], v[192:195], v[144:147], v[66:81]
	v_or_b32_e32 v82, 0xe0, v203
	v_xad_u32 v82, v82, v201, v205
	v_or_b32_e32 v83, 0xf0, v203
	v_xad_u32 v83, v83, v201, v205
	ds_read_b64 v[144:145], v82
	ds_read_b64 v[146:147], v83
	v_cvt_pk_bf16_f32 v148, v10, v11
	v_cvt_pk_bf16_f32 v149, v12, v13
	v_cvt_pk_bf16_f32 v150, v14, v15
	v_cvt_pk_bf16_f32 v151, v16, v17
	v_add_u32_e32 v202, s7, v204
	v_permlane32_swap_b32_e32 v152, v154
	s_waitcnt lgkmcnt(0)
	v_mfma_f32_32x32x16_bf16 v[66:81], v[144:147], v[148:151], v[66:81]
	ds_read_b64_tr_b16 v[144:145], v202 offset:0
	ds_read_b64_tr_b16 v[146:147], v202 offset:0x800
	ds_read_b64_tr_b16 v[148:149], v202 offset:0x1000
	ds_read_b64_tr_b16 v[150:151], v202 offset:0x1800
	s_waitcnt lgkmcnt(0)
	v_permlane32_swap_b32_e32 v153, v155
	v_permlane32_swap_b32_e32 v140, v142
	v_permlane32_swap_b32_e32 v141, v143
	v_add_u32_e32 v82, 0, v200
	v_add_u32_e32 v83, 0x14200, v82
	v_mfma_f32_32x32x16_bf16 v[66:81], v[152:155], v[144:147], v[66:81]
	ds_read_b128 v[152:155], v83
	v_add_u32_e32 v83, 0x14220, v82
	ds_read_b128 v[192:195], v83
	v_add_u32_e32 v83, 0x14240, v82
	ds_read_b128 v[196:199], v83
	v_add_u32_e32 v83, 0x14260, v82
	s_add_i32 s51, 0, 0x4000
	ds_read_b128 v[200:203], v83
	s_waitcnt lgkmcnt(0)
	v_pk_mul_f32 v[50:51], v[50:51], v[152:153]
	v_add_u32_e32 v83, s51, v204
	ds_read_b64_tr_b16 v[152:153], v83 offset:0
	v_pk_mul_f32 v[52:53], v[52:53], v[154:155]
	ds_read_b64_tr_b16 v[154:155], v83 offset:0x800
	v_pk_mul_f32 v[54:55], v[54:55], v[192:193]
	ds_read_b64_tr_b16 v[192:193], v83 offset:0x1000
	v_pk_mul_f32 v[56:57], v[56:57], v[194:195]
	ds_read_b64_tr_b16 v[194:195], v83 offset:0x1800
	s_waitcnt lgkmcnt(0)
	v_pk_mul_f32 v[62:63], v[62:63], v[200:201]
	v_pk_mul_f32 v[58:59], v[58:59], v[196:197]
	v_pk_mul_f32 v[64:65], v[64:65], v[202:203]
	v_pk_mul_f32 v[60:61], v[60:61], v[198:199]
	s_nop 1
	v_mfma_f32_32x32x16_bf16 v[50:65], v[152:155], v[144:147], v[50:65]
	v_add_u32_e32 v152, 0x14280, v82
	ds_read_b128 v[152:155], v152
	v_add_u32_e32 v196, 0x142c0, v82
	v_add_u32_e32 v200, 0x142e0, v82
	ds_read_b128 v[196:199], v196
	ds_read_b128 v[200:203], v200
	s_waitcnt lgkmcnt(0)
	v_pk_mul_f32 v[42:43], v[42:43], v[196:197]
	v_mfma_f32_32x32x16_bf16 v[50:65], v[192:195], v[148:151], v[50:65]
	v_add_u32_e32 v192, 0x142a0, v82
	ds_read_b128 v[192:195], v192
	v_mul_f32_e64 v34, v34, v152
	v_mul_f32_e64 v35, v35, v153
	ds_read_b64_tr_b16 v[152:153], v83 offset:0x200
	v_mul_f32_e64 v36, v36, v154
	v_mul_f32_e64 v37, v37, v155
	ds_read_b64_tr_b16 v[154:155], v83 offset:0xa00
	s_waitcnt lgkmcnt(0)
	v_pk_mul_f32 v[38:39], v[38:39], v[192:193]
	ds_read_b64_tr_b16 v[192:193], v83 offset:0x1200
	v_pk_mul_f32 v[40:41], v[40:41], v[194:195]
	ds_read_b64_tr_b16 v[194:195], v83 offset:0x1a00
	s_waitcnt lgkmcnt(0)
	v_pk_mul_f32 v[46:47], v[46:47], v[200:201]
	v_pk_mul_f32 v[48:49], v[48:49], v[202:203]
	v_pk_mul_f32 v[44:45], v[44:45], v[198:199]
	s_nop 1
	v_mfma_f32_32x32x16_bf16 v[34:49], v[152:155], v[144:147], v[34:49]
	v_add_u32_e32 v152, 0x14300, v82
	ds_read_b128 v[152:155], v152
	v_add_u32_e32 v196, 0x14340, v82
	v_add_u32_e32 v200, 0x14360, v82
	ds_read_b128 v[196:199], v196
	ds_read_b128 v[200:203], v200
	s_waitcnt lgkmcnt(0)
	v_pk_mul_f32 v[26:27], v[26:27], v[196:197]
	v_mfma_f32_32x32x16_bf16 v[34:49], v[192:195], v[148:151], v[34:49]
	v_add_u32_e32 v192, 0x14320, v82
	ds_read_b128 v[192:195], v192
	v_mul_f32_e64 v18, v18, v152
	v_mul_f32_e64 v19, v19, v153
	ds_read_b64_tr_b16 v[152:153], v83 offset:0x400
	v_mul_f32_e64 v20, v20, v154
	v_mul_f32_e64 v21, v21, v155
	ds_read_b64_tr_b16 v[154:155], v83 offset:0xc00
	s_waitcnt lgkmcnt(0)
	v_pk_mul_f32 v[22:23], v[22:23], v[192:193]
	ds_read_b64_tr_b16 v[192:193], v83 offset:0x1400
	v_pk_mul_f32 v[24:25], v[24:25], v[194:195]
	ds_read_b64_tr_b16 v[194:195], v83 offset:0x1c00
	s_waitcnt lgkmcnt(0)
	v_pk_mul_f32 v[30:31], v[30:31], v[200:201]
	v_pk_mul_f32 v[32:33], v[32:33], v[202:203]
	v_pk_mul_f32 v[28:29], v[28:29], v[198:199]
	s_nop 1
	v_mfma_f32_32x32x16_bf16 v[18:33], v[152:155], v[144:147], v[18:33]
	v_add_u32_e32 v152, 0x14380, v82
	ds_read_b128 v[152:155], v152
	v_add_u32_e32 v196, 0x143c0, v82
	ds_read_b128 v[196:199], v196
	s_waitcnt lgkmcnt(0)
	v_pk_mul_f32 v[10:11], v[10:11], v[196:197]
	v_mfma_f32_32x32x16_bf16 v[18:33], v[192:195], v[148:151], v[18:33]
	v_add_u32_e32 v192, 0x143a0, v82
	v_add_u32_e32 v82, 0x143e0, v82
	ds_read_b128 v[192:195], v192
	ds_read_b128 v[200:203], v82
	v_mul_f32_e64 v2, v2, v152
	v_mul_f32_e64 v3, v3, v153
	v_pk_mul_f32 v[4:5], v[4:5], v[154:155]
	v_pk_mul_f32 v[12:13], v[12:13], v[198:199]
	v_mfma_f32_32x32x16_bf16 v[66:81], v[140:143], v[148:151], v[66:81]
	ds_read_b64_tr_b16 v[140:141], v83 offset:0x600
	ds_read_b64_tr_b16 v[142:143], v83 offset:0xe00
	ds_read_b64_tr_b16 v[152:153], v83 offset:0x1600
	ds_read_b64_tr_b16 v[154:155], v83 offset:0x1e00
	s_waitcnt lgkmcnt(0)
	s_waitcnt lgkmcnt(0)
	v_mul_f32_e64 v14, v14, v200
	v_mul_f32_e64 v15, v15, v201
	v_mul_f32_e64 v6, v6, v192
	v_mul_f32_e64 v7, v7, v193
	v_pk_mul_f32 v[16:17], v[16:17], v[202:203]
	v_pk_mul_f32 v[8:9], v[8:9], v[194:195]
	s_and_b64 s[0:1], s[12:13], exec
	s_cselect_b32 s0, s49, s48
	v_lshlrev_b32_e32 v84, 1, v84
	s_lshl_b32 s0, s0, 5
	v_lshl_add_u64 v[82:83], s[28:29], 0, v[84:85]
	v_xor_b32_e32 v84, 31, v86
	s_add_i32 s0, s0, s47
	v_cndmask_b32_e64 v84, v84, v86, s[12:13]
	v_or_b32_e32 v84, s0, v84
	v_lshlrev_b32_e32 v84, 11, v84
	v_mfma_f32_32x32x16_bf16 v[2:17], v[140:143], v[144:147], v[2:17]
	v_cvt_pk_bf16_f32 v66, v66, s0
	v_lshl_add_u64 v[140:141], v[82:83], 0, v[84:85]
	global_store_short v[140:141], v66, off
	v_cvt_pk_bf16_f32 v140, v67, s0
	v_or_b32_e32 v66, 1, v86
	v_xor_b32_e32 v67, 30, v86
	v_cndmask_b32_e64 v66, v67, v66, s[12:13]
	v_or_b32_e32 v66, s0, v66
	v_lshlrev_b32_e32 v84, 11, v66
	v_lshl_add_u64 v[66:67], v[82:83], 0, v[84:85]
	global_store_short v[66:67], v140, off
	v_xor_b32_e32 v66, 29, v86
	v_cndmask_b32_e64 v66, v66, v191, s[12:13]
	v_or_b32_e32 v66, s0, v66
	v_lshlrev_b32_e32 v84, 11, v66
	v_cvt_pk_bf16_f32 v68, v68, s0
	v_lshl_add_u64 v[66:67], v[82:83], 0, v[84:85]
	global_store_short v[66:67], v68, off
	v_xor_b32_e32 v66, 28, v86
	v_cndmask_b32_e64 v66, v66, v190, s[12:13]
	v_or_b32_e32 v66, s0, v66
	v_lshlrev_b32_e32 v84, 11, v66
	v_cvt_pk_bf16_f32 v68, v69, s0
	v_lshl_add_u64 v[66:67], v[82:83], 0, v[84:85]
	global_store_short v[66:67], v68, off
	v_xor_b32_e32 v66, 23, v86
	v_cndmask_b32_e64 v66, v66, v189, s[12:13]
	v_or_b32_e32 v66, s0, v66
	v_lshlrev_b32_e32 v84, 11, v66
	v_cvt_pk_bf16_f32 v68, v70, s0
	v_lshl_add_u64 v[66:67], v[82:83], 0, v[84:85]
	global_store_short v[66:67], v68, off
	v_xor_b32_e32 v66, 22, v86
	v_cndmask_b32_e64 v66, v66, v188, s[12:13]
	v_or_b32_e32 v66, s0, v66
	v_lshlrev_b32_e32 v84, 11, v66
	v_cvt_pk_bf16_f32 v68, v71, s0
	v_lshl_add_u64 v[66:67], v[82:83], 0, v[84:85]
	global_store_short v[66:67], v68, off
	v_xor_b32_e32 v66, 21, v86
	v_cndmask_b32_e64 v66, v66, v187, s[12:13]
	v_or_b32_e32 v66, s0, v66
	v_lshlrev_b32_e32 v84, 11, v66
	v_cvt_pk_bf16_f32 v68, v72, s0
	v_lshl_add_u64 v[66:67], v[82:83], 0, v[84:85]
	global_store_short v[66:67], v68, off
	v_xor_b32_e32 v66, 20, v86
	v_cndmask_b32_e64 v66, v66, v186, s[12:13]
	v_or_b32_e32 v66, s0, v66
	v_lshlrev_b32_e32 v84, 11, v66
	v_cvt_pk_bf16_f32 v68, v73, s0
	v_lshl_add_u64 v[66:67], v[82:83], 0, v[84:85]
	global_store_short v[66:67], v68, off
	v_xor_b32_e32 v66, 15, v86
	v_cndmask_b32_e64 v66, v66, v185, s[12:13]
	v_or_b32_e32 v66, s0, v66
	v_lshlrev_b32_e32 v84, 11, v66
	v_cvt_pk_bf16_f32 v68, v74, s0
	v_lshl_add_u64 v[66:67], v[82:83], 0, v[84:85]
	global_store_short v[66:67], v68, off
	v_xor_b32_e32 v66, 14, v86
	v_cndmask_b32_e64 v66, v66, v184, s[12:13]
	v_or_b32_e32 v66, s0, v66
	v_lshlrev_b32_e32 v84, 11, v66
	v_cvt_pk_bf16_f32 v68, v75, s0
	v_lshl_add_u64 v[66:67], v[82:83], 0, v[84:85]
	global_store_short v[66:67], v68, off
	v_xor_b32_e32 v66, 13, v86
	v_cndmask_b32_e64 v66, v66, v183, s[12:13]
	v_or_b32_e32 v66, s0, v66
	v_lshlrev_b32_e32 v84, 11, v66
	v_cvt_pk_bf16_f32 v68, v76, s0
	v_lshl_add_u64 v[66:67], v[82:83], 0, v[84:85]
	global_store_short v[66:67], v68, off
	v_xor_b32_e32 v66, 12, v86
	v_cndmask_b32_e64 v66, v66, v182, s[12:13]
	v_or_b32_e32 v66, s0, v66
	v_lshlrev_b32_e32 v84, 11, v66
	v_cvt_pk_bf16_f32 v68, v77, s0
	v_lshl_add_u64 v[66:67], v[82:83], 0, v[84:85]
	global_store_short v[66:67], v68, off
	v_xor_b32_e32 v66, 7, v86
	v_cndmask_b32_e64 v66, v66, v181, s[12:13]
	v_or_b32_e32 v66, s0, v66
	v_lshlrev_b32_e32 v84, 11, v66
	v_cvt_pk_bf16_f32 v68, v78, s0
	v_lshl_add_u64 v[66:67], v[82:83], 0, v[84:85]
	global_store_short v[66:67], v68, off
	v_xor_b32_e32 v66, 6, v86
	v_cndmask_b32_e64 v66, v66, v167, s[12:13]
	v_or_b32_e32 v66, s0, v66
	v_lshlrev_b32_e32 v84, 11, v66
	v_cvt_pk_bf16_f32 v68, v79, s0
	v_lshl_add_u64 v[66:67], v[82:83], 0, v[84:85]
	global_store_short v[66:67], v68, off
	v_xor_b32_e32 v66, 5, v86
	v_cndmask_b32_e64 v66, v66, v163, s[12:13]
	v_mfma_f32_32x32x16_bf16 v[2:17], v[152:155], v[148:151], v[2:17]
	v_or_b32_e32 v66, s0, v66
	v_lshlrev_b32_e32 v84, 11, v66
	v_cvt_pk_bf16_f32 v68, v80, s0
	v_lshl_add_u64 v[66:67], v[82:83], 0, v[84:85]
	global_store_short v[66:67], v68, off
	v_xor_b32_e32 v66, 4, v86
	v_cndmask_b32_e64 v66, v66, v87, s[12:13]
	v_or_b32_e32 v66, s0, v66
	v_lshlrev_b32_e32 v84, 11, v66
	v_cvt_pk_bf16_f32 v68, v81, s0
	v_lshl_add_u64 v[66:67], v[82:83], 0, v[84:85]
	v_mov_b32_e32 v82, v159
	s_and_b64 vcc, exec, s[8:9]
	global_store_short v[66:67], v68, off
	s_waitcnt vmcnt(32)
	s_cbranch_vccnz .LBB0_981
	v_cvt_pk_bf16_f32 v66, v132, v133
	v_cvt_pk_bf16_f32 v67, v134, v135
	v_cvt_pk_bf16_f32 v68, v136, v137
	v_cvt_pk_bf16_f32 v69, v138, v139
	v_and_b32_e32 v87, 63, v82
	v_and_b32_e32 v83, 31, v82
	v_mfma_f32_32x32x16_bf16 v[66:81], v[66:69], v[128:131], 0
	s_nop 11
	v_add_f32_e32 v66, v180, v66
	v_mul_f32_e64 v84, |v66|, s40
	v_exp_f32_e32 v84, v84
	v_add_f32_e32 v67, v180, v67
	v_mul_f32_e64 v86, |v67|, s40
	v_exp_f32_e32 v86, v86
	v_add_f32_e32 v84, 1.0, v84
	v_cmp_gt_f32_e32 vcc, s41, v84
	v_min_f32_e32 v66, 0, v66
	v_add_f32_e32 v86, 1.0, v86
	v_cndmask_b32_e64 v140, 0, 32, vcc
	v_ldexp_f32 v84, v84, v140
	v_log_f32_e32 v84, v84
	v_cmp_gt_f32_e64 s[14:15], s41, v86
	v_cndmask_b32_e32 v140, 0, v179, vcc
	v_add_f32_e32 v68, v180, v68
	v_cndmask_b32_e64 v141, 0, 32, s[14:15]
	v_ldexp_f32 v86, v86, v141
	v_mul_f32_e32 v141, 0x3f317217, v84
	v_fma_f32 v141, v84, s42, -v141
	v_fmac_f32_e32 v141, 0x3377d1cf, v84
	v_log_f32_e32 v86, v86
	v_fmac_f32_e32 v141, 0x3f317217, v84
	v_cmp_lt_f32_e64 vcc, |v84|, s43
	s_nop 1
	v_cndmask_b32_e32 v84, v84, v141, vcc
	v_sub_f32_e32 v84, v84, v140
	v_sub_f32_e32 v66, v66, v84
	v_fma_f32 v84, v66, s44, 0
	v_min_f32_e32 v66, 0, v67
	v_mul_f32_e32 v67, 0x3f317217, v86
	v_mul_f32_e64 v140, |v68|, s40
	v_fma_f32 v67, v86, s42, -v67
	v_exp_f32_e32 v140, v140
	v_fmac_f32_e32 v67, 0x3377d1cf, v86
	v_fmac_f32_e32 v67, 0x3f317217, v86
	v_cmp_lt_f32_e64 vcc, |v86|, s43
	s_nop 1
	v_cndmask_b32_e32 v67, v86, v67, vcc
	v_cndmask_b32_e64 v86, 0, v179, s[14:15]
	v_sub_f32_e32 v67, v67, v86
	v_add_f32_e32 v86, 1.0, v140
	v_cmp_gt_f32_e32 vcc, s41, v86
	v_sub_f32_e32 v66, v66, v67
	s_nop 0
	v_cndmask_b32_e64 v140, 0, 32, vcc
	v_ldexp_f32 v86, v86, v140
	v_log_f32_e32 v86, v86
	v_fmamk_f32 v140, v66, 0x3d800000, v84
	v_min_f32_e32 v66, 0, v68
	v_add_f32_e32 v68, v180, v69
	v_mul_f32_e64 v69, |v68|, s40
	v_exp_f32_e32 v69, v69
	v_mul_f32_e32 v67, 0x3f317217, v86
	v_fma_f32 v67, v86, s42, -v67
	v_fmac_f32_e32 v67, 0x3377d1cf, v86
	v_fmac_f32_e32 v67, 0x3f317217, v86
	v_cmp_lt_f32_e64 s[14:15], |v86|, s43
	v_add_f32_e32 v69, 1.0, v69
	s_nop 0
	v_cndmask_b32_e64 v67, v86, v67, s[14:15]
	v_cndmask_b32_e32 v86, 0, v179, vcc
	v_cmp_gt_f32_e32 vcc, s41, v69
	v_sub_f32_e32 v67, v67, v86
	v_sub_f32_e32 v66, v66, v67
	v_cndmask_b32_e64 v86, 0, 32, vcc
	v_ldexp_f32 v69, v69, v86
	v_log_f32_e32 v69, v69
	v_fmamk_f32 v86, v66, 0x3d800000, v140
	v_min_f32_e32 v66, 0, v68
	v_add_f32_e32 v68, v180, v70
	v_mul_f32_e32 v67, 0x3f317217, v69
	v_mul_f32_e64 v70, |v68|, s40
	v_fma_f32 v67, v69, s42, -v67
	v_exp_f32_e32 v70, v70
	v_fmac_f32_e32 v67, 0x3377d1cf, v69
	v_fmac_f32_e32 v67, 0x3f317217, v69
	v_cmp_lt_f32_e64 s[14:15], |v69|, s43
	s_nop 1
	v_cndmask_b32_e64 v67, v69, v67, s[14:15]
	v_cndmask_b32_e32 v69, 0, v179, vcc
	v_sub_f32_e32 v67, v67, v69
	v_add_f32_e32 v69, 1.0, v70
	v_cmp_gt_f32_e32 vcc, s41, v69
	v_sub_f32_e32 v66, v66, v67
	v_min_f32_e32 v67, 0, v68
	v_cndmask_b32_e64 v70, 0, 32, vcc
	v_ldexp_f32 v69, v69, v70
	v_log_f32_e32 v69, v69
	v_add_f32_e32 v70, v180, v71
	v_mul_f32_e64 v71, |v70|, s40
	v_exp_f32_e32 v71, v71
	v_mul_f32_e32 v68, 0x3f317217, v69
	v_fma_f32 v68, v69, s42, -v68
	v_fmac_f32_e32 v68, 0x3377d1cf, v69
	v_fmac_f32_e32 v68, 0x3f317217, v69
	v_cmp_lt_f32_e64 s[14:15], |v69|, s43
	v_fmamk_f32 v66, v66, 0x3d800000, v86
	s_nop 0
	v_cndmask_b32_e64 v68, v69, v68, s[14:15]
	v_cndmask_b32_e32 v69, 0, v179, vcc
	v_sub_f32_e32 v68, v68, v69
	v_add_f32_e32 v69, 1.0, v71
	v_cmp_gt_f32_e32 vcc, s41, v69
	v_sub_f32_e32 v67, v67, v68
	v_fma_f32 v141, v67, s44, 0
	v_cndmask_b32_e64 v71, 0, 32, vcc
	v_ldexp_f32 v69, v69, v71
	v_log_f32_e32 v69, v69
	v_min_f32_e32 v67, 0, v70
	v_add_f32_e32 v70, v180, v72
	v_mul_f32_e64 v71, |v70|, s40
	v_mul_f32_e32 v68, 0x3f317217, v69
	v_fma_f32 v68, v69, s42, -v68
	v_exp_f32_e32 v71, v71
	v_fmac_f32_e32 v68, 0x3377d1cf, v69
	v_fmac_f32_e32 v68, 0x3f317217, v69
	v_cmp_lt_f32_e64 s[14:15], |v69|, s43
	s_nop 1
	v_cndmask_b32_e64 v68, v69, v68, s[14:15]
	v_cndmask_b32_e32 v69, 0, v179, vcc
	v_sub_f32_e32 v68, v68, v69
	v_add_f32_e32 v69, 1.0, v71
	v_cmp_gt_f32_e32 vcc, s41, v69
	v_sub_f32_e32 v67, v67, v68
	v_fmamk_f32 v142, v67, 0x3d800000, v141
	v_cndmask_b32_e64 v71, 0, 32, vcc
	v_ldexp_f32 v69, v69, v71
	v_log_f32_e32 v69, v69
	v_min_f32_e32 v67, 0, v70
	v_add_f32_e32 v70, v180, v73
	v_mul_f32_e64 v71, |v70|, s40
	v_mul_f32_e32 v68, 0x3f317217, v69
	v_fma_f32 v68, v69, s42, -v68
	v_exp_f32_e32 v71, v71
	v_fmac_f32_e32 v68, 0x3377d1cf, v69
	v_fmac_f32_e32 v68, 0x3f317217, v69
	v_cmp_lt_f32_e64 s[14:15], |v69|, s43
	s_nop 1
	v_cndmask_b32_e64 v68, v69, v68, s[14:15]
	v_cndmask_b32_e32 v69, 0, v179, vcc
	v_sub_f32_e32 v68, v68, v69
	v_add_f32_e32 v69, 1.0, v71
	v_cmp_gt_f32_e32 vcc, s41, v69
	v_sub_f32_e32 v67, v67, v68
	v_fmamk_f32 v143, v67, 0x3d800000, v142
	v_cndmask_b32_e64 v71, 0, 32, vcc
	v_ldexp_f32 v69, v69, v71
	v_log_f32_e32 v69, v69
	v_min_f32_e32 v67, 0, v70
	v_add_f32_e32 v70, v180, v74
	v_mul_f32_e64 v71, |v70|, s40
	v_mul_f32_e32 v68, 0x3f317217, v69
	v_fma_f32 v68, v69, s42, -v68
	v_exp_f32_e32 v71, v71
	v_fmac_f32_e32 v68, 0x3377d1cf, v69
	v_fmac_f32_e32 v68, 0x3f317217, v69
	v_cmp_lt_f32_e64 s[14:15], |v69|, s43
	s_nop 1
	v_cndmask_b32_e64 v68, v69, v68, s[14:15]
	v_cndmask_b32_e32 v69, 0, v179, vcc
	v_sub_f32_e32 v68, v68, v69
	v_add_f32_e32 v69, 1.0, v71
	v_cmp_gt_f32_e32 vcc, s41, v69
	v_sub_f32_e32 v67, v67, v68
	v_min_f32_e32 v68, 0, v70
	v_cndmask_b32_e64 v71, 0, 32, vcc
	v_ldexp_f32 v69, v69, v71
	v_log_f32_e32 v69, v69
	v_add_f32_e32 v71, v180, v75
	v_mul_f32_e64 v72, |v71|, s40
	v_exp_f32_e32 v72, v72
	v_mul_f32_e32 v70, 0x3f317217, v69
	v_fma_f32 v70, v69, s42, -v70
	v_fmac_f32_e32 v70, 0x3377d1cf, v69
	v_fmac_f32_e32 v70, 0x3f317217, v69
	v_cmp_lt_f32_e64 s[14:15], |v69|, s43
	v_fmamk_f32 v67, v67, 0x3d800000, v143
	s_nop 0
	v_cndmask_b32_e64 v69, v69, v70, s[14:15]
	v_cndmask_b32_e32 v70, 0, v179, vcc
	v_sub_f32_e32 v69, v69, v70
	v_add_f32_e32 v70, 1.0, v72
	v_cmp_gt_f32_e32 vcc, s41, v70
	v_sub_f32_e32 v68, v68, v69
	v_fma_f32 v75, v68, s44, 0
	v_cndmask_b32_e64 v72, 0, 32, vcc
	v_ldexp_f32 v70, v70, v72
	v_log_f32_e32 v70, v70
	v_min_f32_e32 v68, 0, v71
	v_add_f32_e32 v71, v180, v76
	v_mul_f32_e64 v72, |v71|, s40
	v_mul_f32_e32 v69, 0x3f317217, v70
	v_fma_f32 v69, v70, s42, -v69
	v_exp_f32_e32 v72, v72
	v_fmac_f32_e32 v69, 0x3377d1cf, v70
	v_fmac_f32_e32 v69, 0x3f317217, v70
	v_cmp_lt_f32_e64 s[14:15], |v70|, s43
	s_nop 1
	v_cndmask_b32_e64 v69, v70, v69, s[14:15]
	v_cndmask_b32_e32 v70, 0, v179, vcc
	v_sub_f32_e32 v69, v69, v70
	v_add_f32_e32 v70, 1.0, v72
	v_cmp_gt_f32_e32 vcc, s41, v70
	v_sub_f32_e32 v68, v68, v69
	v_fmamk_f32 v76, v68, 0x3d800000, v75
	v_cndmask_b32_e64 v72, 0, 32, vcc
	v_ldexp_f32 v70, v70, v72
	v_log_f32_e32 v70, v70
	v_min_f32_e32 v68, 0, v71
	v_add_f32_e32 v71, v180, v77
	v_mul_f32_e64 v72, |v71|, s40
	v_mul_f32_e32 v69, 0x3f317217, v70
	v_fma_f32 v69, v70, s42, -v69
	v_exp_f32_e32 v72, v72
	v_fmac_f32_e32 v69, 0x3377d1cf, v70
	v_fmac_f32_e32 v69, 0x3f317217, v70
	v_cmp_lt_f32_e64 s[14:15], |v70|, s43
	s_nop 1
	v_cndmask_b32_e64 v69, v70, v69, s[14:15]
	v_cndmask_b32_e32 v70, 0, v179, vcc
	v_sub_f32_e32 v69, v69, v70
	v_add_f32_e32 v70, 1.0, v72
	v_cmp_gt_f32_e32 vcc, s41, v70
	v_sub_f32_e32 v68, v68, v69
	v_fmamk_f32 v77, v68, 0x3d800000, v76
	v_cndmask_b32_e64 v72, 0, 32, vcc
	v_ldexp_f32 v70, v70, v72
	v_log_f32_e32 v70, v70
	v_min_f32_e32 v68, 0, v71
	v_add_f32_e32 v71, v180, v78
	v_mul_f32_e64 v72, |v71|, s40
	v_mul_f32_e32 v69, 0x3f317217, v70
	v_fma_f32 v69, v70, s42, -v69
	v_exp_f32_e32 v72, v72
	v_fmac_f32_e32 v69, 0x3377d1cf, v70
	v_fmac_f32_e32 v69, 0x3f317217, v70
	v_cmp_lt_f32_e64 s[14:15], |v70|, s43
	s_nop 1
	v_cndmask_b32_e64 v69, v70, v69, s[14:15]
	v_cndmask_b32_e32 v70, 0, v179, vcc
	v_sub_f32_e32 v69, v69, v70
	v_add_f32_e32 v70, 1.0, v72
	v_cmp_gt_f32_e32 vcc, s41, v70
	v_sub_f32_e32 v68, v68, v69
	v_min_f32_e32 v69, 0, v71
	v_cndmask_b32_e64 v72, 0, 32, vcc
	v_ldexp_f32 v70, v70, v72
	v_log_f32_e32 v70, v70
	v_add_f32_e32 v72, v180, v79
	v_mul_f32_e64 v73, |v72|, s40
	v_exp_f32_e32 v73, v73
	v_mul_f32_e32 v71, 0x3f317217, v70
	v_fma_f32 v71, v70, s42, -v71
	v_fmac_f32_e32 v71, 0x3377d1cf, v70
	v_fmac_f32_e32 v71, 0x3f317217, v70
	v_cmp_lt_f32_e64 s[14:15], |v70|, s43
	v_fmamk_f32 v68, v68, 0x3d800000, v77
	s_nop 0
	v_cndmask_b32_e64 v70, v70, v71, s[14:15]
	v_cndmask_b32_e32 v71, 0, v179, vcc
	v_sub_f32_e32 v70, v70, v71
	v_add_f32_e32 v71, 1.0, v73
	v_cmp_gt_f32_e32 vcc, s41, v71
	v_sub_f32_e32 v69, v69, v70
	v_fma_f32 v78, v69, s44, 0
	v_cndmask_b32_e64 v73, 0, 32, vcc
	v_ldexp_f32 v71, v71, v73
	v_log_f32_e32 v71, v71
	v_min_f32_e32 v69, 0, v72
	v_add_f32_e32 v72, v180, v80
	v_mul_f32_e64 v73, |v72|, s40
	v_mul_f32_e32 v70, 0x3f317217, v71
	v_fma_f32 v70, v71, s42, -v70
	v_exp_f32_e32 v73, v73
	v_fmac_f32_e32 v70, 0x3377d1cf, v71
	v_fmac_f32_e32 v70, 0x3f317217, v71
	v_cmp_lt_f32_e64 s[14:15], |v71|, s43
	s_nop 1
	v_cndmask_b32_e64 v70, v71, v70, s[14:15]
	v_cndmask_b32_e32 v71, 0, v179, vcc
	v_sub_f32_e32 v70, v70, v71
	v_add_f32_e32 v71, 1.0, v73
	v_cmp_gt_f32_e32 vcc, s41, v71
	v_sub_f32_e32 v69, v69, v70
	v_fmamk_f32 v79, v69, 0x3d800000, v78
	v_cndmask_b32_e64 v73, 0, 32, vcc
	v_ldexp_f32 v71, v71, v73
	v_log_f32_e32 v71, v71
	v_min_f32_e32 v69, 0, v72
	v_add_f32_e32 v72, v180, v81
	v_mul_f32_e64 v73, |v72|, s40
	v_mul_f32_e32 v70, 0x3f317217, v71
	v_fma_f32 v70, v71, s42, -v70
	v_exp_f32_e32 v73, v73
	v_fmac_f32_e32 v70, 0x3377d1cf, v71
	v_fmac_f32_e32 v70, 0x3f317217, v71
	v_cmp_lt_f32_e64 s[14:15], |v71|, s43
	s_nop 1
	v_cndmask_b32_e64 v70, v71, v70, s[14:15]
	v_cndmask_b32_e32 v71, 0, v179, vcc
	v_sub_f32_e32 v70, v70, v71
	v_add_f32_e32 v71, 1.0, v73
	v_cmp_gt_f32_e32 vcc, s41, v71
	v_sub_f32_e32 v69, v69, v70
	v_fmamk_f32 v80, v69, 0x3d800000, v79
	v_cndmask_b32_e64 v73, 0, 32, vcc
	v_ldexp_f32 v71, v71, v73
	v_log_f32_e32 v71, v71
	v_min_f32_e32 v69, 0, v72
	v_mov_b32_e32 v72, v67
	v_mov_b32_e32 v73, v68
	v_mul_f32_e32 v70, 0x3f317217, v71
	v_fma_f32 v70, v71, s42, -v70
	v_fmac_f32_e32 v70, 0x3377d1cf, v71
	v_fmac_f32_e32 v70, 0x3f317217, v71
	v_cmp_lt_f32_e64 s[14:15], |v71|, s43
	s_nop 1
	v_cndmask_b32_e64 v70, v71, v70, s[14:15]
	v_cndmask_b32_e32 v71, 0, v179, vcc
	v_sub_f32_e32 v70, v70, v71
	v_sub_f32_e32 v69, v69, v70
	v_mov_b32_e32 v70, v66
	v_mov_b32_e32 v71, v66
	s_nop 1
	v_permlane32_swap_b32_e32 v70, v71
	v_cmp_gt_u32_e32 vcc, 32, v87
	v_fmamk_f32 v69, v69, 0x3d800000, v80
	v_mov_b32_e32 v74, v69
	v_cndmask_b32_e32 v70, v70, v71, vcc
	v_mov_b32_e32 v71, v67
	s_nop 1
	v_permlane32_swap_b32_e32 v71, v72
	v_cndmask_b32_e32 v71, v71, v72, vcc
	v_mov_b32_e32 v72, v68
	s_nop 1
	v_permlane32_swap_b32_e32 v72, v73
	v_cndmask_b32_e32 v72, v72, v73, vcc
	v_mov_b32_e32 v73, v69
	s_nop 1
	v_permlane32_swap_b32_e32 v73, v74
	v_cndmask_b32_e32 v74, v73, v74, vcc
	v_lshlrev_b32_e32 v73, 6, v82
	v_cndmask_b32_e64 v81, v70, 0, vcc
	v_and_b32_e32 v82, 0x800, v73
	v_lshlrev_b32_e32 v73, 2, v83
	v_add_f32_e32 v83, v81, v84
	v_add3_u32 v82, s4, v73, v82
	v_add_f32_e32 v84, v81, v140
	ds_write2st64_b32 v82, v83, v84 offset1:2
	v_add_f32_e32 v83, v81, v86
	v_add_f32_e32 v84, v81, v66
	ds_write2st64_b32 v82, v83, v84 offset0:4 offset1:6
	v_cndmask_b32_e32 v83, v71, v70, vcc
	v_add_f32_e32 v83, v83, v66
	v_add_f32_e32 v81, v81, v83
	v_add_f32_e32 v83, v141, v81
	v_add_f32_e32 v84, v142, v81
	ds_write2st64_b32 v82, v83, v84 offset0:16 offset1:18
	v_add_f32_e32 v83, v143, v81
	v_add_f32_e32 v84, v67, v81
	ds_write2st64_b32 v82, v83, v84 offset0:20 offset1:22
	v_cndmask_b32_e32 v83, v72, v71, vcc
	v_add_f32_e32 v83, v83, v67
	v_add_f32_e32 v81, v83, v81
	v_add_f32_e32 v75, v75, v81
	v_add_f32_e32 v76, v76, v81
	ds_write2st64_b32 v82, v75, v76 offset0:32 offset1:34
	v_add_f32_e32 v75, v77, v81
	v_add_f32_e32 v76, v68, v81
	ds_write2st64_b32 v82, v75, v76 offset0:36 offset1:38
	v_cndmask_b32_e32 v75, v74, v72, vcc
	v_add_f32_e32 v75, v75, v68
	v_add_f32_e32 v75, v75, v81
	v_add_f32_e32 v76, v78, v75
	v_add_f32_e32 v77, v79, v75
	ds_write2st64_b32 v82, v76, v77 offset0:48 offset1:50
	v_add_f32_e32 v76, v80, v75
	v_add_f32_e32 v75, v69, v75
	ds_write2st64_b32 v82, v76, v75 offset0:52 offset1:54
	s_and_saveexec_b64 s[14:15], vcc
	s_cbranch_execz .LBB0_980
	v_add_f32_e32 v66, v66, v67
	v_add_f32_e32 v67, v68, v69
	v_add_f32_e32 v66, v66, v67
	v_add_f32_e32 v67, v70, v71
	v_add_f32_e32 v66, v67, v66
	v_add_f32_e32 v67, v72, v74
	v_add_f32_e32 v66, v67, v66
	v_mul_f32_e32 v67, 0x3fb8aa3b, v66
	v_exp_f32_e32 v67, v67
	v_add_u32_e32 v68, s5, v73
	ds_write_b32 v68, v66
	v_add_u32_e32 v66, s10, v73
	ds_write_b32 v66, v67

.LBB0_981:
	v_mov_b32_e32 v66, v159
	s_waitcnt lgkmcnt(0)
	s_barrier
	v_and_b32_e32 v144, 0xffff0000, v112
	v_ashrrev_i32_e32 v67, 5, v66
	v_lshlrev_b32_e32 v68, 10, v66
	v_and_b32_e32 v70, 0xfffff0, v67
	v_lshlrev_b32_e32 v71, 1, v67
	v_and_b32_e32 v69, 0x4000, v68
	v_lshlrev_b32_e32 v68, 3, v66
	v_and_or_b32 v70, v71, 8, v70
	v_lshrrev_b32_e32 v71, 1, v67
	v_and_b32_e32 v73, 3, v67
	v_lshrrev_b32_e32 v70, 1, v70
	v_bfe_u32 v72, v68, 5, 2
	v_and_or_b32 v71, v71, 4, v73
	v_or_b32_e32 v70, v70, v72
	v_lshlrev_b32_e32 v71, 6, v71
	v_lshlrev_b32_e32 v73, 4, v66
	v_lshlrev_b32_e32 v70, 9, v70
	v_and_b32_e32 v73, 48, v73
	v_add3_u32 v71, 0, v69, v71
	v_add3_u32 v69, v71, v70, v73
	ds_write_b128 v69, v[120:123] offset:32768
	v_add_u32_e32 v69, 16, v67
	v_and_b32_e32 v70, 0xfffff0, v69
	v_lshlrev_b32_e32 v74, 1, v69
	v_and_or_b32 v70, v74, 8, v70
	v_lshrrev_b32_e32 v70, 1, v70
	v_or_b32_e32 v70, v70, v72
	v_lshlrev_b32_e32 v70, 9, v70
	v_add3_u32 v70, v71, v70, v73
	ds_write_b128 v70, v[124:127] offset:32768
	v_ashrrev_i32_e32 v70, 4, v66
	v_and_b32_e32 v71, 15, v66
	v_lshlrev_b32_e32 v72, 9, v70
	v_lshlrev_b32_e32 v73, 5, v71
	v_add3_u32 v76, s50, v72, v73
	v_add_u32_e32 v72, 0, v73
	v_add_u32_e32 v84, 0x14000, v72
	ds_read_b128 v[72:75], v76
	ds_read_b128 v[76:79], v76 offset:16
	ds_read_b128 v[80:83], v84
	ds_read_b128 v[140:143], v84 offset:16
	v_lshlrev_b32_e32 v84, 16, v112
	s_waitcnt lgkmcnt(0)
	v_mul_f32_e32 v72, 0x3fb8aa3b, v72
	v_exp_f32_e32 v72, v72
	v_mul_f32_e32 v73, 0x3fb8aa3b, v73
	v_mul_f32_e32 v74, 0x3fb8aa3b, v74
	v_mul_f32_e32 v75, 0x3fb8aa3b, v75
	v_mul_f32_e32 v76, 0x3fb8aa3b, v76
	v_mul_f32_e32 v77, 0x3fb8aa3b, v77
	v_exp_f32_e32 v73, v73
	v_exp_f32_e32 v74, v74
	v_exp_f32_e32 v75, v75
	v_exp_f32_e32 v76, v76
	v_exp_f32_e32 v77, v77
	v_mul_f32_e32 v78, 0x3fb8aa3b, v78
	v_mul_f32_e32 v79, 0x3fb8aa3b, v79
	v_exp_f32_e32 v78, v78
	v_exp_f32_e32 v79, v79
	v_lshlrev_b32_e32 v145, 16, v113
	v_and_b32_e32 v146, 0xffff0000, v113
	v_lshlrev_b32_e32 v147, 16, v114
	v_and_b32_e32 v148, 0xffff0000, v114
	v_rcp_f32_e32 v86, v72
	v_mul_f32_e32 v72, v72, v84
	v_mul_f32_e32 v84, 0x3fb8aa3b, v140
	v_rcp_f32_e32 v87, v73
	v_mul_f32_e32 v73, v73, v144
	v_rcp_f32_e32 v144, v74
	v_mul_f32_e32 v74, v74, v145
	v_rcp_f32_e32 v145, v75
	v_mul_f32_e32 v75, v75, v146
	v_rcp_f32_e32 v146, v76
	v_mul_f32_e32 v76, v76, v147
	v_exp_f32_e32 v140, v84
	v_rcp_f32_e32 v147, v77
	v_mul_f32_e32 v77, v77, v148
	v_mul_f32_e32 v84, 0x3fb8aa3b, v141
	v_lshlrev_b32_e32 v149, 16, v115
	v_and_b32_e32 v150, 0xffff0000, v115
	v_mul_f32_e32 v80, 0x3fb8aa3b, v80
	v_mul_f32_e32 v81, 0x3fb8aa3b, v81
	v_exp_f32_e32 v141, v84
	v_mul_f32_e32 v84, 0x3fb8aa3b, v142
	v_cvt_pk_bf16_f32 v72, v72, v73
	v_cvt_pk_bf16_f32 v73, v74, v75
	v_cvt_pk_bf16_f32 v74, v76, v77
	v_lshlrev_b32_e32 v76, 8, v70
	v_lshlrev_b32_e32 v71, 4, v71
	v_and_b32_e32 v77, 0x70, v66
	v_exp_f32_e32 v80, v80
	v_exp_f32_e32 v81, v81
	v_rcp_f32_e32 v148, v78
	v_mul_f32_e32 v78, v78, v149
	v_exp_f32_e32 v142, v84
	v_rcp_f32_e32 v149, v79
	v_mul_f32_e32 v79, v79, v150
	v_mul_f32_e32 v84, 0x3fb8aa3b, v143
	v_bitop3_b32 v76, v71, v76, v77 bitop3:0xde
	v_exp_f32_e32 v143, v84
	v_cvt_pk_bf16_f32 v75, v78, v79
	v_add_u32_e32 v84, 0, v76
	v_mul_f32_e32 v82, 0x3fb8aa3b, v82
	v_mul_f32_e32 v83, 0x3fb8aa3b, v83
	ds_write_b128 v84, v[72:75]
	v_lshlrev_b32_e32 v72, 16, v116
	v_and_b32_e32 v73, 0xffff0000, v116
	v_exp_f32_e32 v82, v82
	v_exp_f32_e32 v83, v83
	v_pk_mul_f32 v[72:73], v[86:87], v[72:73]
	v_and_b32_e32 v71, 48, v71
	v_pk_mul_f32 v[74:75], v[72:73], v[80:81]
	v_cvt_pk_bf16_f32 v72, v72, v73
	v_cvt_pk_bf16_f32 v76, v74, v75
	v_lshlrev_b32_e32 v74, 16, v117
	v_and_b32_e32 v75, 0xffff0000, v117
	v_pk_mul_f32 v[74:75], v[144:145], v[74:75]
	v_lshlrev_b32_e32 v80, 16, v119
	v_pk_mul_f32 v[78:79], v[74:75], v[82:83]
	v_cvt_pk_bf16_f32 v73, v74, v75
	v_lshlrev_b32_e32 v74, 16, v118
	v_and_b32_e32 v75, 0xffff0000, v118
	v_and_b32_e32 v81, 0xffff0000, v119
	v_pk_mul_f32 v[74:75], v[146:147], v[74:75]
	v_pk_mul_f32 v[80:81], v[148:149], v[80:81]
	v_cvt_pk_bf16_f32 v77, v78, v79
	v_pk_mul_f32 v[78:79], v[74:75], v[140:141]
	v_cvt_pk_bf16_f32 v74, v74, v75
	v_cvt_pk_bf16_f32 v75, v80, v81
	ds_write_b128 v84, v[72:75] offset:8192
	v_and_b32_e32 v72, 0xfffff0, v70
	v_lshlrev_b32_e32 v73, 1, v70
	v_and_or_b32 v72, v73, 8, v72
	v_lshrrev_b32_e32 v72, 1, v72
	v_bfe_u32 v74, v66, 2, 2
	v_lshrrev_b32_e32 v73, 1, v70
	v_or_b32_e32 v72, v72, v74
	v_and_b32_e32 v74, 3, v70
	v_and_or_b32 v73, v73, 4, v74
	v_pk_mul_f32 v[82:83], v[80:81], v[142:143]
	v_lshlrev_b32_e32 v73, 6, v73
	v_lshl_add_u32 v72, v72, 9, 0
	v_cvt_pk_bf16_f32 v78, v78, v79
	v_cvt_pk_bf16_f32 v79, v82, v83
	v_add3_u32 v71, v72, v73, v71
	s_andn2_b64 vcc, exec, s[36:37]
	ds_write_b128 v71, v[76:79] offset:16384
	s_cbranch_vccnz .LBB0_969
	s_add_i32 s14, s48, -3
	s_and_b64 s[0:1], s[12:13], exec
	s_cselect_b32 s0, s20, s14
	s_lshl_b32 s0, s0, 5
	v_sub_u32_e32 v71, 31, v70
	v_cndmask_b32_e64 v70, v71, v70, s[12:13]
	s_add_i32 s0, s0, s47
	v_and_b32_e32 v72, 0x78, v68
	v_add_u32_e32 v73, s0, v70
	v_mov_b64_e32 v[70:71], s[30:31]
	v_mad_i64_i32 v[70:71], s[14:15], v73, s39, v[70:71]
	v_lshlrev_b32_e32 v84, 1, v72
	v_lshl_add_u64 v[70:71], v[70:71], 0, v[84:85]
	global_load_dwordx4 v[112:115], v[70:71], off
	global_load_dwordx4 v[116:119], v[70:71], off offset:1024
	v_sub_u32_e32 v70, 31, v67
	v_cndmask_b32_e64 v70, v70, v67, s[12:13]
	v_sub_u32_e32 v67, 15, v67
	v_add_u32_e32 v72, s0, v70
	v_mov_b64_e32 v[70:71], s[34:35]
	v_and_b32_e32 v68, 0xf8, v68
	v_cndmask_b32_e64 v67, v67, v69, s[12:13]
	v_mad_i64_i32 v[72:73], s[14:15], v72, s39, v[70:71]
	v_lshlrev_b32_e32 v84, 1, v68
	v_add_u32_e32 v67, s0, v67
	v_lshl_add_u64 v[72:73], v[72:73], 0, v[84:85]
	v_mad_i64_i32 v[68:69], s[14:15], v67, s39, v[70:71]
	v_lshl_add_u64 v[68:69], v[68:69], 0, v[84:85]
	global_load_dwordx4 v[120:123], v[72:73], off offset:2048
	global_load_dwordx4 v[124:127], v[68:69], off offset:2048
	s_and_b64 vcc, exec, s[8:9]
	s_cbranch_vccnz .LBB0_969
	v_and_b32_e32 v67, 31, v66
	v_bitop3_b32 v68, v66, 31, v66 bitop3:0xc
	v_cndmask_b32_e64 v67, v68, v67, s[12:13]
	v_or_b32_e32 v67, s0, v67
	v_lshlrev_b32_e32 v84, 7, v67
	v_lshl_add_u64 v[68:69], s[26:27], 0, v[84:85]
	v_and_b32_e32 v84, 32, v66
	v_lshl_add_u64 v[66:67], v[68:69], 0, v[84:85]
	global_load_dwordx4 v[132:135], v[66:67], off
	global_load_dwordx4 v[136:139], v[66:67], off offset:16
	s_branch .LBB0_969
